# GEMM k-loops rotated: loop-back barrier is the loop head, k-counter / exit test / next stage+M0 computed before it; tile prologue barrier replaced by the head barrier
# speedup vs baseline: 1.0086x; 1.0086x over previous
; __device__ __forceinline__ int opaque_tid() { int t = threadIdx.x; asm volatile("" : "+v"(t)); return t; }
; __device__ __forceinline__ void gemm_mainloop_d(const bf16_t* __restrict__ Ap, int lda, const bf16_t* __restrict__ Bt, int K,
;                                                 int m0, int n0, f32x4 (&acc)[4][4], char* lds) {
;   const int tid = opaque_tid(), lane = tid & 63, wid = tid >> 6, wr = wid >> 1, wc = wid & 1, fr = lane & 15, fq = lane >> 4;
; #pragma unroll
;   for (int m = 0; m < 4; m++)
; #pragma unroll
;     for (int n = 0; n < 4; n++) acc[m][n] = (f32x4){0.f, 0.f, 0.f, 0.f};
;   const int nk = K >> 6;
;   const int lrow = tid >> 3, cph = tid & 7;
;   auto dma = [&](int kt, int st) {
;     char* la = lds + st * 32768; char* lb = la + 16384;
; #pragma unroll
;     for (int i = 0; i < 4; i++) {
;       const int row = i * 32 + lrow; const int c = cph ^ ((row >> 1) & 7);
;       __builtin_amdgcn_global_load_lds((const unsigned*)(Ap + (size_t)(m0 + row) * lda + kt * 64 + c * 8), (__attribute__((address_space(3))) unsigned*)(la + i * 4096 + tid * 16), 16, 0, 0);
;       __builtin_amdgcn_global_load_lds((const unsigned*)(Bt + (size_t)(n0 + row) * K + kt * 64 + c * 8), (__attribute__((address_space(3))) unsigned*)(lb + i * 4096 + tid * 16), 16, 0, 0);
;     }
;   };
;   dma(0, 0);
;   asm volatile("s_waitcnt vmcnt(0)" ::: "memory"); __builtin_amdgcn_s_barrier(); asm volatile("" ::: "memory");
.LBB0_94:
	s_and_b32 s29, s35, 0xffffff80
	s_and_b32 s37, s34, 0x380
	s_mov_b32 s40, 0
	s_add_u32 s2, s46, s40
	s_addc_u32 s3, s47, 0
	s_add_u32 s24, s2, 0x768000
	s_addc_u32 s25, s3, 0
	s_mov_b32 s41, 0
	s_add_u32 s2, s46, s41
	s_addc_u32 s3, s47, 0
	s_add_u32 s38, s2, 0xf3cc000
	s_mov_b32 s27, 0
	s_mov_b32 s28, 0
	v_mov_b32_e32 v8, v198
	s_addc_u32 s39, s3, 0
	s_lshl_b32 s2, s36, 4
	s_and_b32 s3, s2, 0xffffff80
	v_ashrrev_i32_e32 v11, 3, v8
	v_lshrrev_b32_e32 v12, 1, v11
	v_xor_b32_e32 v2, v12, v8
	s_waitcnt vmcnt(5)
	v_add_u32_e32 v4, s3, v11
	s_waitcnt vmcnt(4)
	v_mov_b64_e32 v[0:1], s[24:25]
	v_mad_i64_i32 v[4:5], s[24:25], v4, s33, v[0:1]
	v_lshlrev_b32_e32 v2, 4, v2
	v_lshl_add_u32 v82, v8, 4, 0
	s_lshl_b32 s2, s36, 7
	v_and_b32_e32 v2, 0x70, v2
	v_readfirstlane_b32 s24, v82
	s_and_b32 s2, s2, 0x380
	v_lshl_add_u64 v[4:5], v[4:5], 0, v[2:3]
	s_mov_b32 m0, s24
	v_add_u32_e32 v6, s2, v11
	global_load_lds_dwordx4 v[4:5], off
	v_mov_b64_e32 v[4:5], s[38:39]
	v_mad_i64_i32 v[6:7], s[24:25], v6, s33, v[4:5]
	v_add_u32_e32 v13, 0x4000, v82
	v_lshl_add_u64 v[6:7], v[6:7], 0, v[2:3]
	v_readfirstlane_b32 s24, v13
	s_mov_b32 m0, s24
	v_add_u32_e32 v13, 32, v11
	global_load_lds_dwordx4 v[6:7], off
	v_add_u32_e32 v6, s3, v13
	v_mad_i64_i32 v[6:7], s[24:25], v6, s33, v[0:1]
	v_add_u32_e32 v14, 0x1000, v82
	v_lshl_add_u64 v[6:7], v[6:7], 0, v[2:3]
	v_readfirstlane_b32 s24, v14
	s_mov_b32 m0, s24
	v_add_u32_e32 v14, 0x5000, v82
	global_load_lds_dwordx4 v[6:7], off
	v_add_u32_e32 v6, s2, v13
	v_mad_i64_i32 v[6:7], s[24:25], v6, s33, v[4:5]
	v_readfirstlane_b32 s24, v14
	v_lshl_add_u64 v[6:7], v[6:7], 0, v[2:3]
	s_mov_b32 m0, s24
	v_add_u32_e32 v14, 64, v11
	global_load_lds_dwordx4 v[6:7], off
	v_add_u32_e32 v6, s3, v14
	v_mad_i64_i32 v[6:7], s[24:25], v6, s33, v[0:1]
	v_add_u32_e32 v15, 0x2000, v82
	v_lshl_add_u64 v[6:7], v[6:7], 0, v[2:3]
	v_readfirstlane_b32 s24, v15
	s_mov_b32 m0, s24
	v_add_u32_e32 v15, 0x6000, v82
	global_load_lds_dwordx4 v[6:7], off
	v_add_u32_e32 v6, s2, v14
	v_mad_i64_i32 v[6:7], s[24:25], v6, s33, v[4:5]
	v_readfirstlane_b32 s24, v15
	v_lshl_add_u64 v[6:7], v[6:7], 0, v[2:3]
	s_mov_b32 m0, s24
	s_mov_b32 s4, 0x1ffffc0
	global_load_lds_dwordx4 v[6:7], off
	v_add_u32_e32 v6, 0x60, v11
	v_add_u32_e32 v7, s3, v6
	v_mad_i64_i32 v[0:1], s[24:25], v7, s33, v[0:1]
	v_add_u32_e32 v7, 0x3000, v82
	v_lshl_add_u64 v[0:1], v[0:1], 0, v[2:3]
	v_readfirstlane_b32 s24, v7
	s_mov_b32 m0, s24
	v_lshrrev_b32_e32 v9, 4, v8
	global_load_lds_dwordx4 v[0:1], off
	v_add_u32_e32 v0, s2, v6
	v_mad_i64_i32 v[0:1], s[24:25], v0, s33, v[4:5]
	v_lshl_add_u64 v[0:1], v[0:1], 0, v[2:3]
	v_add_u32_e32 v2, 0x7000, v82
	v_bfe_u32 v10, v8, 4, 2
	v_readfirstlane_b32 s24, v2
	s_mov_b32 m0, s24
	v_lshlrev_b32_e32 v2, 7, v8
	global_load_lds_dwordx4 v[0:1], off
	v_and_b32_e32 v0, 15, v8
	v_lshrrev_b32_e32 v1, 1, v8
	v_and_or_b32 v0, v1, s4, v0
	v_bfe_u32 v1, v8, 1, 3
	v_bitop3_b32 v4, v9, v1, 3 bitop3:0x6c
	v_bitop3_b32 v1, v10, v1, 4 bitop3:0x36
	v_lshlrev_b32_e32 v4, 4, v4
	v_lshlrev_b32_e32 v0, 7, v0
	v_lshlrev_b32_e32 v1, 4, v1
	v_and_b32_e32 v2, 0x2780, v2
	v_or_b32_e32 v85, v0, v4
	v_or_b32_e32 v83, v1, v0
	v_add_u32_e32 v0, s29, v11
	v_or_b32_e32 v84, v4, v2
	v_or_b32_e32 v2, v1, v2
	v_mad_i64_i32 v[0:1], s[24:25], v0, s33, 0
	v_bitop3_b32 v4, v12, 7, v8 bitop3:0x48
	v_readlane_b32 s4, v254, 39
	v_lshlrev_b32_e32 v7, 4, v4
	s_add_u32 s24, s4, s40
	v_readlane_b32 s4, v254, 40
	v_add_u32_e32 v4, s37, v11
	s_addc_u32 s25, s4, 0
	v_mad_i64_i32 v[4:5], s[38:39], v4, s33, 0
	v_readlane_b32 s4, v254, 41
	s_add_u32 s38, s4, s41
	v_readlane_b32 s4, v254, 42
	v_or_b32_e32 v4, v4, v7
	s_addc_u32 s39, s4, 0
	s_waitcnt vmcnt(0)
	v_lshl_add_u64 v[68:69], s[38:39], 0, v[4:5]
	v_add_u32_e32 v4, s29, v13
	v_mad_i64_i32 v[4:5], s[40:41], v4, s33, 0
	v_or_b32_e32 v4, v4, v7
	v_lshl_add_u64 v[70:71], s[24:25], 0, v[4:5]
	v_add_u32_e32 v4, s37, v13
	v_mad_i64_i32 v[4:5], s[40:41], v4, s33, 0
	v_or_b32_e32 v4, v4, v7
	v_lshl_add_u64 v[72:73], s[38:39], 0, v[4:5]
	v_add_u32_e32 v4, s29, v14
	v_mad_i64_i32 v[4:5], s[40:41], v4, s33, 0
	v_or_b32_e32 v4, v4, v7
	v_lshl_add_u64 v[74:75], s[24:25], 0, v[4:5]
	v_add_u32_e32 v4, s37, v14
	v_mad_i64_i32 v[4:5], s[40:41], v4, s33, 0
	v_or_b32_e32 v4, v4, v7
	v_lshl_add_u64 v[76:77], s[38:39], 0, v[4:5]
	v_add_u32_e32 v4, s29, v6
	v_mad_i64_i32 v[4:5], s[40:41], v4, s33, 0
	v_or_b32_e32 v4, v4, v7
	v_or_b32_e32 v0, v0, v7
	v_lshl_add_u64 v[78:79], s[24:25], 0, v[4:5]
	v_add_u32_e32 v4, s37, v6
	v_lshl_add_u64 v[0:1], s[24:25], 0, v[0:1]
	v_mad_i64_i32 v[4:5], s[24:25], v4, s33, 0
	s_waitcnt vmcnt(0)
	v_or_b32_e32 v4, v4, v7
	v_lshl_add_u64 v[80:81], s[38:39], 0, v[4:5]
	v_mov_b32_e32 v4, 0
	s_mov_b32 s26, 0
	s_mov_b64 s[24:25], 0
	v_mov_b32_e32 v5, v4
	v_mov_b32_e32 v6, v4
	v_mov_b32_e32 v7, v4
	v_mov_b32_e32 v8, v4
	v_mov_b32_e32 v9, v4
	v_mov_b32_e32 v10, v4
	v_mov_b32_e32 v11, v4
	v_mov_b32_e32 v12, v4
	v_mov_b32_e32 v13, v4
	v_mov_b32_e32 v14, v4
	v_mov_b32_e32 v15, v4
	v_mov_b32_e32 v16, v4
	v_mov_b32_e32 v17, v4
	v_mov_b32_e32 v18, v4
	v_mov_b32_e32 v19, v4
	v_mov_b32_e32 v20, v4
	v_mov_b32_e32 v21, v4
	v_mov_b32_e32 v22, v4
	v_mov_b32_e32 v23, v4
	v_mov_b32_e32 v24, v4
	v_mov_b32_e32 v25, v4
	v_mov_b32_e32 v26, v4
	v_mov_b32_e32 v27, v4
	v_mov_b32_e32 v28, v4
	v_mov_b32_e32 v29, v4
	v_mov_b32_e32 v30, v4
	v_mov_b32_e32 v31, v4
	v_mov_b32_e32 v32, v4
	v_mov_b32_e32 v33, v4
	v_mov_b32_e32 v34, v4
	v_mov_b32_e32 v35, v4
	v_mov_b32_e32 v36, v4
	v_mov_b32_e32 v37, v4
	v_mov_b32_e32 v38, v4
	v_mov_b32_e32 v39, v4
	v_mov_b32_e32 v40, v4
	v_mov_b32_e32 v41, v4
	v_mov_b32_e32 v42, v4
	v_mov_b32_e32 v43, v4
	v_mov_b32_e32 v44, v4
	v_mov_b32_e32 v45, v4
	v_mov_b32_e32 v46, v4
	v_mov_b32_e32 v47, v4
	v_mov_b32_e32 v48, v4
	v_mov_b32_e32 v49, v4
	v_mov_b32_e32 v50, v4
	v_mov_b32_e32 v51, v4
	v_mov_b32_e32 v52, v4
	v_mov_b32_e32 v53, v4
	v_mov_b32_e32 v54, v4
	v_mov_b32_e32 v55, v4
	v_mov_b32_e32 v56, v4
	v_mov_b32_e32 v57, v4
	v_mov_b32_e32 v58, v4
	v_mov_b32_e32 v59, v4
	v_mov_b32_e32 v60, v4
	v_mov_b32_e32 v61, v4
	v_mov_b32_e32 v62, v4
	v_mov_b32_e32 v63, v4
	v_mov_b32_e32 v64, v4
	v_mov_b32_e32 v65, v4
	v_mov_b32_e32 v66, v4
	v_mov_b32_e32 v67, v4
	v_subrev_u32_e32 v150, s46, v0
	v_subrev_u32_e32 v151, s46, v68
	v_subrev_u32_e32 v152, s46, v70
	v_subrev_u32_e32 v153, s46, v72
	v_subrev_u32_e32 v154, s46, v74
	v_subrev_u32_e32 v155, s46, v76
	v_subrev_u32_e32 v156, s46, v78
	v_subrev_u32_e32 v157, s46, v80
	v_readfirstlane_b32 vcc_hi, v82
	s_and_b32 s29, s26, 0x8000
	s_xor_b32 s37, s29, 0x8000
	s_add_i32 s37, s37, vcc_hi
; __device__ __forceinline__ void gemm_mainloop_d(const bf16_t* __restrict__ Ap, int lda, const bf16_t* __restrict__ Bt, int K,
;                                                 int m0, int n0, f32x4 (&acc)[4][4], char* lds) {
;     ...
;   for (int kt = 0; kt < nk; kt++) {
;     const int st = kt & 1;
;     if (kt + 1 < nk) dma(kt + 1, st ^ 1);
;     const char* la = lds + st * 32768; const char* lb = la + 16384;
;     bf16x8 af[2][4], bfv[2][4];
; #pragma unroll
;     for (int kc = 0; kc < 2; kc++) {
; #pragma unroll
;       for (int m = 0; m < 4; m++) { const int row = wr * 64 + m * 16 + fr; af[kc][m] = *(const bf16x8*)(la + (row * 8 + ((kc * 4 + fq) ^ ((row >> 1) & 7))) * 16); }
; #pragma unroll
;       for (int n = 0; n < 4; n++) { const int row = wc * 64 + n * 16 + fr; bfv[kc][n] = *(const bf16x8*)(lb + (row * 8 + ((kc * 4 + fq) ^ ((row >> 1) & 7))) * 16); }
;     }
;     __builtin_amdgcn_s_setprio(1);
; #pragma unroll
;     for (int kc = 0; kc < 2; kc++)
; #pragma unroll
;       for (int m = 0; m < 4; m++)
; #pragma unroll
;         for (int n = 0; n < 4; n++) acc[m][n] = __builtin_amdgcn_mfma_f32_16x16x32_bf16(bfv[kc][n], af[kc][m], acc[m][n], 0, 0, 0);
;     __builtin_amdgcn_s_setprio(0);
;     asm volatile("s_waitcnt vmcnt(0) lgkmcnt(0)" ::: "memory"); __builtin_amdgcn_s_barrier(); asm volatile("" ::: "memory");
;   }
.LBB0_95:
	s_barrier
	s_setprio 3
	s_mov_b32 m0, s37
	s_add_i32 vcc_lo, s37, 0x4000
	global_load_lds_dwordx4 v150, s[46:47]
	s_mov_b32 m0, vcc_lo
	s_add_i32 vcc_lo, s37, 0x1000
	global_load_lds_dwordx4 v151, s[46:47]
	s_mov_b32 m0, vcc_lo
	s_add_i32 vcc_lo, s37, 0x5000
	global_load_lds_dwordx4 v152, s[46:47]
	s_mov_b32 m0, vcc_lo
	s_add_i32 vcc_lo, s37, 0x2000
	global_load_lds_dwordx4 v153, s[46:47]
	s_mov_b32 m0, vcc_lo
	s_add_i32 vcc_lo, s37, 0x6000
	global_load_lds_dwordx4 v154, s[46:47]
	s_mov_b32 m0, vcc_lo
	s_add_i32 vcc_lo, s37, 0x3000
	global_load_lds_dwordx4 v155, s[46:47]
	s_mov_b32 m0, vcc_lo
	s_add_i32 vcc_lo, s37, 0x7000
	global_load_lds_dwordx4 v156, s[46:47]
	s_mov_b32 m0, vcc_lo
	s_nop 0
	global_load_lds_dwordx4 v157, s[46:47]
	v_add_u32_e32 v150, 0x80, v150
	v_add_u32_e32 v151, 0x80, v151
	v_add_u32_e32 v152, 0x80, v152
	v_add_u32_e32 v153, 0x80, v153
	v_add_u32_e32 v154, 0x80, v154
	v_add_u32_e32 v155, 0x80, v155
	v_add_u32_e32 v156, 0x80, v156
	v_add_u32_e32 v157, 0x80, v157
	v_add_u32_e32 v98, s29, v85
	v_add_u32_e32 v114, s29, v84
	v_add_u32_e32 v130, s29, v83
	v_add_u32_e32 v146, s29, v2
	ds_read_b128 v[86:89], v98
	ds_read_b128 v[90:93], v98 offset:2048
	ds_read_b128 v[94:97], v98 offset:4096
	ds_read_b128 v[98:101], v98 offset:6144
	ds_read_b128 v[102:105], v114 offset:16384
	ds_read_b128 v[106:109], v114 offset:18432
	ds_read_b128 v[110:113], v114 offset:20480
	ds_read_b128 v[114:117], v114 offset:22528
	ds_read_b128 v[118:121], v130
	ds_read_b128 v[122:125], v130 offset:2048
	ds_read_b128 v[126:129], v130 offset:4096
	ds_read_b128 v[130:133], v130 offset:6144
	ds_read_b128 v[134:137], v146 offset:16384
	ds_read_b128 v[138:141], v146 offset:18432
	ds_read_b128 v[142:145], v146 offset:20480
	ds_read_b128 v[146:149], v146 offset:22528
	s_setprio 1
	s_waitcnt lgkmcnt(0)
	v_mfma_f32_16x16x32_bf16 v[64:67], v[102:105], v[86:89], v[64:67]
	v_mfma_f32_16x16x32_bf16 v[60:63], v[106:109], v[86:89], v[60:63]
	v_mfma_f32_16x16x32_bf16 v[56:59], v[110:113], v[86:89], v[56:59]
	v_mfma_f32_16x16x32_bf16 v[52:55], v[114:117], v[86:89], v[52:55]
	v_mfma_f32_16x16x32_bf16 v[48:51], v[102:105], v[90:93], v[48:51]
	v_mfma_f32_16x16x32_bf16 v[44:47], v[106:109], v[90:93], v[44:47]
	v_mfma_f32_16x16x32_bf16 v[40:43], v[110:113], v[90:93], v[40:43]
	v_mfma_f32_16x16x32_bf16 v[36:39], v[114:117], v[90:93], v[36:39]
	v_mfma_f32_16x16x32_bf16 v[32:35], v[102:105], v[94:97], v[32:35]
	v_mfma_f32_16x16x32_bf16 v[28:31], v[106:109], v[94:97], v[28:31]
	v_mfma_f32_16x16x32_bf16 v[24:27], v[110:113], v[94:97], v[24:27]
	v_mfma_f32_16x16x32_bf16 v[20:23], v[114:117], v[94:97], v[20:23]
	v_mfma_f32_16x16x32_bf16 v[16:19], v[102:105], v[98:101], v[16:19]
	v_mfma_f32_16x16x32_bf16 v[12:15], v[106:109], v[98:101], v[12:15]
	v_mfma_f32_16x16x32_bf16 v[8:11], v[110:113], v[98:101], v[8:11]
	v_mfma_f32_16x16x32_bf16 v[4:7], v[114:117], v[98:101], v[4:7]
	v_mfma_f32_16x16x32_bf16 v[64:67], v[134:137], v[118:121], v[64:67]
	v_mfma_f32_16x16x32_bf16 v[60:63], v[138:141], v[118:121], v[60:63]
	v_mfma_f32_16x16x32_bf16 v[56:59], v[142:145], v[118:121], v[56:59]
	v_mfma_f32_16x16x32_bf16 v[52:55], v[146:149], v[118:121], v[52:55]
	v_mfma_f32_16x16x32_bf16 v[48:51], v[134:137], v[122:125], v[48:51]
	v_mfma_f32_16x16x32_bf16 v[44:47], v[138:141], v[122:125], v[44:47]
	v_mfma_f32_16x16x32_bf16 v[40:43], v[142:145], v[122:125], v[40:43]
	v_mfma_f32_16x16x32_bf16 v[36:39], v[146:149], v[122:125], v[36:39]
	v_mfma_f32_16x16x32_bf16 v[32:35], v[134:137], v[126:129], v[32:35]
	v_mfma_f32_16x16x32_bf16 v[28:31], v[138:141], v[126:129], v[28:31]
	v_mfma_f32_16x16x32_bf16 v[24:27], v[142:145], v[126:129], v[24:27]
	v_mfma_f32_16x16x32_bf16 v[20:23], v[146:149], v[126:129], v[20:23]
	v_mfma_f32_16x16x32_bf16 v[16:19], v[134:137], v[130:133], v[16:19]
	v_mfma_f32_16x16x32_bf16 v[12:15], v[138:141], v[130:133], v[12:15]
	v_mfma_f32_16x16x32_bf16 v[8:11], v[142:145], v[130:133], v[8:11]
	v_mfma_f32_16x16x32_bf16 v[4:7], v[146:149], v[130:133], v[4:7]
	s_setprio 0
	s_waitcnt vmcnt(0) lgkmcnt(0)
	s_add_u32 s24, s24, 0x80
	s_addc_u32 s25, s25, 0
	s_add_i32 s26, s26, 0x8000
	s_and_b32 s29, s26, 0x8000
	s_xor_b32 s37, s29, 0x8000
	s_add_i32 s37, s37, vcc_hi
	s_cmpk_eq_i32 s24, 0x1580
	s_cbranch_scc0 .LBB0_95
	s_barrier
; __device__ __forceinline__ void gemm_mainloop_d(const bf16_t* __restrict__ Ap, int lda, const bf16_t* __restrict__ Bt, int K,
;                                                 int m0, int n0, f32x4 (&acc)[4][4], char* lds) {
;     ...
;     const char* la = lds + st * 32768; const char* lb = la + 16384;
;     bf16x8 af[2][4], bfv[2][4];
; #pragma unroll
;     for (int kc = 0; kc < 2; kc++) {
; #pragma unroll
;       for (int m = 0; m < 4; m++) { const int row = wr * 64 + m * 16 + fr; af[kc][m] = *(const bf16x8*)(la + (row * 8 + ((kc * 4 + fq) ^ ((row >> 1) & 7))) * 16); }
; #pragma unroll
;       for (int n = 0; n < 4; n++) { const int row = wc * 64 + n * 16 + fr; bfv[kc][n] = *(const bf16x8*)(lb + (row * 8 + ((kc * 4 + fq) ^ ((row >> 1) & 7))) * 16); }
;     }
;     __builtin_amdgcn_s_setprio(1);
; #pragma unroll
;     for (int kc = 0; kc < 2; kc++)
; #pragma unroll
;       for (int m = 0; m < 4; m++)
; #pragma unroll
;         for (int n = 0; n < 4; n++) acc[m][n] = __builtin_amdgcn_mfma_f32_16x16x32_bf16(bfv[kc][n], af[kc][m], acc[m][n], 0, 0, 0);
;     __builtin_amdgcn_s_setprio(0);
;     asm volatile("s_waitcnt vmcnt(0) lgkmcnt(0)" ::: "memory"); __builtin_amdgcn_s_barrier(); asm volatile("" ::: "memory");
	v_add_u32_e32 v0, 0, v85
	ds_read_b128 v[68:71], v0 offset:32768
	ds_read_b128 v[72:75], v0 offset:34816
	ds_read_b128 v[76:79], v0 offset:36864
	ds_read_b128 v[86:89], v0 offset:38912
	v_add_u32_e32 v0, 0, v84
	ds_read_b128 v[90:93], v0 offset:49152
	ds_read_b128 v[94:97], v0 offset:51200
	ds_read_b128 v[98:101], v0 offset:53248
	ds_read_b128 v[102:105], v0 offset:55296
	v_add_u32_e32 v0, 0, v83
	s_add_u32 s24, s46, s27
	ds_read_b128 v[80:83], v0 offset:32768
	ds_read_b128 v[106:109], v0 offset:34816
	ds_read_b128 v[110:113], v0 offset:36864
	ds_read_b128 v[114:117], v0 offset:38912
	v_add_u32_e32 v0, 0, v2
	s_addc_u32 s25, s47, 0
	ds_read_b128 v[118:121], v0 offset:49152
	ds_read_b128 v[122:125], v0 offset:51200
	ds_read_b128 v[126:129], v0 offset:53248
	ds_read_b128 v[130:133], v0 offset:55296
	s_add_u32 s28, s46, s28
	s_addc_u32 s29, s47, 0
	s_add_u32 s26, s24, 0x65a8000
	s_addc_u32 s27, s25, 0
	s_add_u32 s24, s28, 0xff8c000
	s_addc_u32 s25, s29, 0
	s_setprio 1
	s_waitcnt lgkmcnt(0)
	v_mfma_f32_16x16x32_bf16 v[56:59], v[98:101], v[68:71], v[56:59]
	v_mfma_f32_16x16x32_bf16 v[48:51], v[90:93], v[72:75], v[48:51]
	v_mfma_f32_16x16x32_bf16 v[44:47], v[94:97], v[72:75], v[44:47]
	v_mfma_f32_16x16x32_bf16 v[40:43], v[98:101], v[72:75], v[40:43]
	v_mfma_f32_16x16x32_bf16 v[36:39], v[102:105], v[72:75], v[36:39]
	v_mfma_f32_16x16x32_bf16 v[32:35], v[90:93], v[76:79], v[32:35]
	v_mfma_f32_16x16x32_bf16 v[28:31], v[94:97], v[76:79], v[28:31]
	v_mfma_f32_16x16x32_bf16 v[24:27], v[98:101], v[76:79], v[24:27]
	v_mfma_f32_16x16x32_bf16 v[20:23], v[102:105], v[76:79], v[20:23]
	v_mfma_f32_16x16x32_bf16 v[16:19], v[90:93], v[86:89], v[16:19]
	v_mfma_f32_16x16x32_bf16 v[12:15], v[94:97], v[86:89], v[12:15]
	v_mfma_f32_16x16x32_bf16 v[8:11], v[98:101], v[86:89], v[8:11]
	v_mfma_f32_16x16x32_bf16 v[4:7], v[102:105], v[86:89], v[4:7]
	v_mfma_f32_16x16x32_bf16 v[64:67], v[90:93], v[68:71], v[64:67]
	v_mfma_f32_16x16x32_bf16 v[60:63], v[94:97], v[68:71], v[60:63]
	v_mfma_f32_16x16x32_bf16 v[52:55], v[102:105], v[68:71], v[52:55]
	v_mfma_f32_16x16x32_bf16 v[56:59], v[126:129], v[80:83], v[56:59]
	v_mfma_f32_16x16x32_bf16 v[48:51], v[118:121], v[106:109], v[48:51]
	v_mfma_f32_16x16x32_bf16 v[44:47], v[122:125], v[106:109], v[44:47]
	v_mfma_f32_16x16x32_bf16 v[40:43], v[126:129], v[106:109], v[40:43]
	v_mfma_f32_16x16x32_bf16 v[36:39], v[130:133], v[106:109], v[36:39]
	v_mfma_f32_16x16x32_bf16 v[32:35], v[118:121], v[110:113], v[32:35]
	v_mfma_f32_16x16x32_bf16 v[28:31], v[122:125], v[110:113], v[28:31]
	v_mfma_f32_16x16x32_bf16 v[24:27], v[126:129], v[110:113], v[24:27]
	v_mfma_f32_16x16x32_bf16 v[20:23], v[130:133], v[110:113], v[20:23]
	v_mfma_f32_16x16x32_bf16 v[16:19], v[118:121], v[114:117], v[16:19]
	v_mfma_f32_16x16x32_bf16 v[12:15], v[122:125], v[114:117], v[12:15]
	v_mfma_f32_16x16x32_bf16 v[8:11], v[126:129], v[114:117], v[8:11]
	v_mfma_f32_16x16x32_bf16 v[4:7], v[130:133], v[114:117], v[4:7]
	v_mfma_f32_16x16x32_bf16 v[64:67], v[118:121], v[80:83], v[64:67]
	v_mfma_f32_16x16x32_bf16 v[60:63], v[122:125], v[80:83], v[60:63]
	v_mfma_f32_16x16x32_bf16 v[68:71], v[130:133], v[80:83], v[52:55]
	s_setprio 0
	v_mov_b32_e32 v0, v198
	s_waitcnt vmcnt(0) lgkmcnt(0)
	s_barrier
; __device__ __forceinline__ unsigned pk2(float lo, float hi) { unsigned r; asm("v_cvt_pk_bf16_f32 %0, %1, %2" : "=v"(r) : "v"(lo), "v"(hi)); return r; }
; __device__ __forceinline__ float bflo(unsigned u) { return __uint_as_float(u << 16); }
; __device__ __forceinline__ float bfhi(unsigned u) { return __uint_as_float(u & 0xffff0000u); }
; __device__ __forceinline__ void gemm_RES(const bf16_t* A, int K, const bf16_t* Bt, const float* xin, float* xout, bf16_t* xb, float* rss, int item, char* lds) {
;     ...
; #pragma unroll
;   for (int m = 0; m < 4; m++) {
;     const int rowg = m0 + wr * 64 + m * 16 + fr;
;     const size_t ro = (size_t)rowg * DM;
;     float sq = 0.f;
; #pragma unroll
;     for (int n = 0; n < 4; n++) {
;       const int col = n0 + wc * 64 + n * 16 + fq * 4;
;       f32x4 xv = *(const f32x4*)(xin + ro + col);
;       const f32x4 xn = xv + acc[m][n];
;       *(f32x4*)(xout + ro + col) = xn;
;       u32x2 w; w[0] = pk2(xn[0], xn[1]); w[1] = pk2(xn[2], xn[3]); *(u32x2*)(xb + ro + col) = w;
;       const float b0 = bflo(w[0]), b1 = bfhi(w[0]), b2 = bflo(w[1]), b3 = bfhi(w[1]);
;       sq += b0 * b0 + b1 * b1 + b2 * b2 + b3 * b3;
;     }
;     sq += __shfl_xor(sq, 16); sq += __shfl_xor(sq, 32);
;     if (fq == 0) unsafeAtomicAdd(rss + rowg, sq);
;   }
	v_readlane_b32 s4, v252, 35
	v_ashrrev_i32_e32 v2, 1, v0
	v_and_b32_e32 v2, 0xffffffc0, v2
	v_bfe_u32 v80, v0, 4, 2
	v_add_u32_e32 v2, s3, v2
	v_and_b32_e32 v1, 64, v0
	v_and_or_b32 v0, v0, 15, v2
	v_lshlrev_b32_e32 v2, 2, v80
	v_or3_b32 v54, v2, v1, s2
	v_ashrrev_i32_e32 v1, 31, v0
	v_lshlrev_b64 v[52:53], 12, v[0:1]
	v_readlane_b32 s18, v252, 49
	v_readlane_b32 s19, v252, 50
	v_lshlrev_b32_e32 v2, 2, v54
	v_readlane_b32 s5, v252, 36
	v_lshl_add_u64 v[52:53], s[18:19], 0, v[52:53]
	v_lshl_add_u64 v[76:77], v[52:53], 0, v[2:3]
	global_load_dwordx4 v[72:75], v[76:77], off
	v_lshlrev_b32_e32 v52, 1, v54
	v_lshlrev_b64 v[54:55], 11, v[0:1]
	v_mov_b32_e32 v53, v3
	v_lshl_add_u64 v[54:55], s[26:27], 0, v[54:55]
	v_lshl_add_u64 v[78:79], v[54:55], 0, v[52:53]
	v_readlane_b32 s6, v252, 37
	v_readlane_b32 s7, v252, 38
	v_readlane_b32 s8, v252, 39
	v_readlane_b32 s9, v252, 40
	v_readlane_b32 s10, v252, 41
	v_readlane_b32 s11, v252, 42
	v_readlane_b32 s12, v252, 43
	v_readlane_b32 s13, v252, 44
	v_readlane_b32 s14, v252, 45
	v_readlane_b32 s15, v252, 46
	v_readlane_b32 s16, v252, 47
	v_readlane_b32 s17, v252, 48
	s_waitcnt vmcnt(0)
	v_pk_add_f32 v[66:67], v[66:67], v[74:75]
	v_pk_add_f32 v[64:65], v[64:65], v[72:73]
	global_store_dwordx4 v[76:77], v[64:67], off
	v_cvt_pk_bf16_f32 v54, v64, v65
	v_cvt_pk_bf16_f32 v55, v66, v67
	global_store_dwordx2 v[78:79], v[54:55], off
	global_load_dwordx4 v[64:67], v[76:77], off offset:64
	s_waitcnt vmcnt(0)
	v_pk_add_f32 v[62:63], v[62:63], v[66:67]
	v_pk_add_f32 v[60:61], v[60:61], v[64:65]
	global_store_dwordx4 v[76:77], v[60:63], off offset:64
	v_cvt_pk_bf16_f32 v64, v60, v61
	v_cvt_pk_bf16_f32 v65, v62, v63
	global_store_dwordx2 v[78:79], v[64:65], off offset:32
	global_load_dwordx4 v[60:63], v[76:77], off offset:128
	v_lshlrev_b32_e32 v66, 16, v54
	v_and_b32_e32 v54, 0xffff0000, v54
	v_mul_f32_e32 v54, v54, v54
	v_lshlrev_b32_e32 v67, 16, v55
	v_fmac_f32_e32 v54, v66, v66
	v_and_b32_e32 v55, 0xffff0000, v55
	v_fmac_f32_e32 v54, v67, v67
	v_fmac_f32_e32 v54, v55, v55
	v_lshlrev_b32_e32 v55, 16, v64
	v_and_b32_e32 v64, 0xffff0000, v64
	v_mul_f32_e32 v64, v64, v64
	v_lshlrev_b32_e32 v66, 16, v65
	v_fmac_f32_e32 v64, v55, v55
	v_and_b32_e32 v65, 0xffff0000, v65
	v_fmac_f32_e32 v64, v66, v66
	v_fmac_f32_e32 v64, v65, v65
	v_add_f32_e32 v54, v54, v64
	s_waitcnt vmcnt(0)
	v_pk_add_f32 v[58:59], v[58:59], v[62:63]
	v_pk_add_f32 v[56:57], v[56:57], v[60:61]
	global_store_dwordx4 v[76:77], v[56:59], off offset:128
	v_cvt_pk_bf16_f32 v62, v56, v57
	v_cvt_pk_bf16_f32 v63, v58, v59
	global_store_dwordx2 v[78:79], v[62:63], off offset:64
	global_load_dwordx4 v[58:61], v[76:77], off offset:192
	v_lshlrev_b32_e32 v55, 16, v62
	v_and_b32_e32 v62, 0xffff0000, v62
	v_mul_f32_e32 v62, v62, v62
	v_lshlrev_b32_e32 v64, 16, v63
	v_fmac_f32_e32 v62, v55, v55
	v_and_b32_e32 v63, 0xffff0000, v63
	v_fmac_f32_e32 v62, v64, v64
	v_fmac_f32_e32 v62, v63, v63
	v_add_f32_e32 v54, v54, v62
	v_and_b32_e32 v57, 64, v218
	v_xor_b32_e32 v56, 16, v218
	v_add_u32_e32 v57, 64, v57
	v_cmp_lt_i32_e32 vcc, v56, v57
	s_waitcnt vmcnt(0)
	v_pk_add_f32 v[58:59], v[68:69], v[58:59]
	s_nop 0
	v_cvt_pk_bf16_f32 v62, v58, v59
	v_pk_add_f32 v[60:61], v[70:71], v[60:61]
	v_and_b32_e32 v64, 0xffff0000, v62
	v_lshlrev_b32_e32 v55, 16, v62
	v_mul_f32_e32 v64, v64, v64
	v_cvt_pk_bf16_f32 v63, v60, v61
	v_fmac_f32_e32 v64, v55, v55
	v_lshlrev_b32_e32 v65, 16, v63
	v_and_b32_e32 v66, 0xffff0000, v63
	v_fmac_f32_e32 v64, v65, v65
	v_cndmask_b32_e32 v56, v218, v56, vcc
	v_fmac_f32_e32 v64, v66, v66
	v_lshlrev_b32_e32 v56, 2, v56
	v_add_f32_e32 v54, v54, v64
	ds_bpermute_b32 v55, v56, v54
	v_xor_b32_e32 v64, 32, v218
	v_cmp_lt_i32_e32 vcc, v64, v57
	global_store_dwordx4 v[76:77], v[58:61], off offset:192
	global_store_dwordx2 v[78:79], v[62:63], off offset:96
	v_cndmask_b32_e32 v57, v218, v64, vcc
	s_waitcnt lgkmcnt(0)
	v_add_f32_e32 v54, v54, v55
	v_lshlrev_b32_e32 v57, 2, v57
	ds_bpermute_b32 v55, v57, v54
	v_cmp_eq_u32_e32 vcc, 0, v80
	s_and_saveexec_b64 s[28:29], vcc
	s_cbranch_execz .LBB0_98
	v_lshl_add_u64 v[58:59], v[0:1], 2, s[24:25]
	s_waitcnt lgkmcnt(0)
	v_add_f32_e32 v1, v54, v55
	global_atomic_add_f32 v[58:59], v1, off

; __device__ __forceinline__ unsigned char* WS(const Params& p) { unsigned z = 0; asm volatile("" : "+s"(z)); return p.ws + z; }
; __device__ __forceinline__ void gemm_mainloop_d(const bf16_t* __restrict__ Ap, int lda, const bf16_t* __restrict__ Bt, int K,
;                                                 int m0, int n0, f32x4 (&acc)[4][4], char* lds) {
;     ...
;   auto dma = [&](int kt, int st) {
;     char* la = lds + st * 32768; char* lb = la + 16384;
; #pragma unroll
;     for (int i = 0; i < 4; i++) {
;       const int row = i * 32 + lrow; const int c = cph ^ ((row >> 1) & 7);
;       __builtin_amdgcn_global_load_lds((const unsigned*)(Ap + (size_t)(m0 + row) * lda + kt * 64 + c * 8), (__attribute__((address_space(3))) unsigned*)(la + i * 4096 + tid * 16), 16, 0, 0);
;       __builtin_amdgcn_global_load_lds((const unsigned*)(Bt + (size_t)(n0 + row) * K + kt * 64 + c * 8), (__attribute__((address_space(3))) unsigned*)(lb + i * 4096 + tid * 16), 16, 0, 0);
;     }
;   };
;   dma(0, 0);
;   asm volatile("s_waitcnt vmcnt(0)" ::: "memory"); __builtin_amdgcn_s_barrier(); asm volatile("" ::: "memory");
; __device__ __forceinline__ void gemm_GU(const Params& p, int item, char* lds) {
;   const int r_ = item >> 9, x_ = item & 7, y_ = (item >> 3) & 63;
;   const int pid = (r_ * 8 + x_) * 2 + (y_ >> 5), t32 = y_ & 31;
;   const int mt = (pid / 11) * 8 + (t32 >> 2), nt = (pid % 11) * 4 + (t32 & 3); const int m0 = mt * 128, n0 = nt * 128;
;   f32x4 acc[4][4];
;   gemm_mainloop_d((const bf16_t*)(WS(p) + OFF_XB), DM, (const bf16_t*)(WS(p) + OFF_WGU), DM, m0, n0, acc, lds);
.LBB0_108:
	s_ashr_i32 s25, s30, 6
	s_and_b32 s24, s30, 7
	s_and_b32 s25, s25, 0x7ffffff8
	s_or_b32 s24, s25, s24
	s_lshl_b32 s24, s24, 1
	s_bfe_u32 s25, s30, 0x10008
	s_or_b32 s38, s24, s25
	s_mul_hi_i32 s24, s38, 0x2e8ba2e9
	s_lshr_b32 s25, s24, 31
	s_ashr_i32 s24, s24, 1
	s_add_i32 s39, s24, s25
	s_mul_i32 s24, s39, 11
	s_sub_i32 s25, s38, s24
	s_lshl_b32 s24, s30, 2
	s_lshl_b32 s26, s30, 4
	s_lshl_b32 s40, s39, 10
	s_and_b32 s24, s24, 0x380
	s_lshl_b32 s25, s25, 9
	s_and_b32 s26, s26, 0x180
	s_and_b32 s36, s29, 0x380
	s_and_b32 s37, s28, 0x180
	s_or_b32 s24, s40, s24
	s_or_b32 s31, s25, s26
	s_mov_b32 s41, 0
	s_mov_b32 s42, 0
	s_waitcnt vmcnt(5)
	v_mov_b32_e32 v4, v198
	s_add_u32 s26, s46, s41
	s_addc_u32 s27, s47, 0
	v_ashrrev_i32_e32 v7, 3, v4
	v_lshrrev_b32_e32 v8, 1, v7
	s_waitcnt vmcnt(4)
	v_add_u32_e32 v0, s24, v7
	s_add_u32 s34, s26, 0x65a8000
	v_xor_b32_e32 v2, v8, v4
	v_ashrrev_i32_e32 v1, 31, v0
	s_addc_u32 s35, s27, 0
	v_lshlrev_b64 v[0:1], 11, v[0:1]
	v_lshlrev_b32_e32 v2, 4, v2
	v_lshl_add_u32 v82, v4, 4, 0
	v_lshl_add_u64 v[0:1], s[34:35], 0, v[0:1]
	v_and_b32_e32 v2, 0x70, v2
	v_readfirstlane_b32 s43, v82
	s_add_u32 s26, s46, s42
	v_lshl_add_u64 v[0:1], v[0:1], 0, v[2:3]
	s_mov_b32 m0, s43
	s_addc_u32 s27, s47, 0
	global_load_lds_dwordx4 v[0:1], off
	v_add_u32_e32 v0, s31, v7
	s_add_u32 s26, s26, 0xe8cc000
	v_ashrrev_i32_e32 v1, 31, v0
	s_addc_u32 s27, s27, 0
	v_lshlrev_b64 v[0:1], 11, v[0:1]
	v_add_u32_e32 v9, 0x4000, v82
	v_lshl_add_u64 v[0:1], s[26:27], 0, v[0:1]
	v_readfirstlane_b32 s43, v9
	v_lshl_add_u64 v[0:1], v[0:1], 0, v[2:3]
	s_mov_b32 m0, s43
	v_add_u32_e32 v9, 32, v7
	global_load_lds_dwordx4 v[0:1], off
	v_add_u32_e32 v0, s24, v9
	v_ashrrev_i32_e32 v1, 31, v0
	v_lshlrev_b64 v[0:1], 11, v[0:1]
	v_add_u32_e32 v10, 0x1000, v82
	v_lshl_add_u64 v[0:1], s[34:35], 0, v[0:1]
	v_readfirstlane_b32 s43, v10
	v_lshl_add_u64 v[0:1], v[0:1], 0, v[2:3]
	s_mov_b32 m0, s43
	v_add_u32_e32 v10, 0x5000, v82
	global_load_lds_dwordx4 v[0:1], off
	v_add_u32_e32 v0, s31, v9
	v_ashrrev_i32_e32 v1, 31, v0
	v_lshlrev_b64 v[0:1], 11, v[0:1]
	v_lshl_add_u64 v[0:1], s[26:27], 0, v[0:1]
	v_readfirstlane_b32 s43, v10
	v_lshl_add_u64 v[0:1], v[0:1], 0, v[2:3]
	s_mov_b32 m0, s43
	v_add_u32_e32 v10, 64, v7
	global_load_lds_dwordx4 v[0:1], off
	v_add_u32_e32 v0, s24, v10
	v_ashrrev_i32_e32 v1, 31, v0
	v_lshlrev_b64 v[0:1], 11, v[0:1]
	v_add_u32_e32 v11, 0x2000, v82
	v_lshl_add_u64 v[0:1], s[34:35], 0, v[0:1]
	v_readfirstlane_b32 s43, v11
	v_lshl_add_u64 v[0:1], v[0:1], 0, v[2:3]
	s_mov_b32 m0, s43
	v_add_u32_e32 v11, 0x6000, v82
	global_load_lds_dwordx4 v[0:1], off
	v_add_u32_e32 v0, s31, v10
	v_ashrrev_i32_e32 v1, 31, v0
	v_lshlrev_b64 v[0:1], 11, v[0:1]
	v_lshl_add_u64 v[0:1], s[26:27], 0, v[0:1]
	v_readfirstlane_b32 s43, v11
	v_lshl_add_u64 v[0:1], v[0:1], 0, v[2:3]
	s_mov_b32 m0, s43
	v_add_u32_e32 v11, 0x60, v7
	global_load_lds_dwordx4 v[0:1], off
	v_add_u32_e32 v0, s24, v11
	v_ashrrev_i32_e32 v1, 31, v0
	v_lshlrev_b64 v[0:1], 11, v[0:1]
	v_add_u32_e32 v12, 0x3000, v82
	v_lshl_add_u64 v[0:1], s[34:35], 0, v[0:1]
	v_readfirstlane_b32 s34, v12
	v_lshl_add_u64 v[0:1], v[0:1], 0, v[2:3]
	s_mov_b32 m0, s34
	s_mov_b32 s4, 0x1ffffc0
	global_load_lds_dwordx4 v[0:1], off
	v_add_u32_e32 v0, s31, v11
	v_ashrrev_i32_e32 v1, 31, v0
	v_lshlrev_b64 v[0:1], 11, v[0:1]
	v_lshl_add_u64 v[0:1], s[26:27], 0, v[0:1]
	v_lshl_add_u64 v[0:1], v[0:1], 0, v[2:3]
	v_add_u32_e32 v2, 0x7000, v82
	s_or_b32 s36, s36, s40
	v_readfirstlane_b32 s26, v2
	s_mov_b32 m0, s26
	v_lshrrev_b32_e32 v5, 4, v4
	global_load_lds_dwordx4 v[0:1], off
	v_and_b32_e32 v0, 15, v4
	v_lshrrev_b32_e32 v1, 1, v4
	v_and_or_b32 v0, v1, s4, v0
	v_readlane_b32 s4, v254, 44
	s_add_u32 s26, s4, s41
	v_readlane_b32 s4, v254, 45
	s_addc_u32 s27, s4, 0
	s_lshl_b32 s34, s38, 9
	v_bfe_u32 v6, v4, 4, 2
	v_bfe_u32 v1, v4, 1, 3
	v_lshlrev_b32_e32 v2, 7, v4
	v_bitop3_b32 v4, v8, 7, v4 bitop3:0x48
	s_or_b32 s37, s37, s34
	v_bitop3_b32 v5, v5, v1, 3 bitop3:0x6c
	v_bitop3_b32 v1, v6, v1, 4 bitop3:0x36
	v_lshlrev_b32_e32 v6, 4, v4
	v_add_u32_e32 v4, s37, v7
	s_mulk_i32 s39, 0x1600
	v_and_b32_e32 v2, 0x2780, v2
	v_lshlrev_b32_e32 v5, 4, v5
	v_lshlrev_b32_e32 v0, 7, v0
	v_subrev_u32_e32 v4, s39, v4
	v_or_b32_e32 v85, v0, v5
	v_or_b32_e32 v84, v5, v2
	v_ashrrev_i32_e32 v5, 31, v4
	v_readlane_b32 s4, v254, 47
	v_lshlrev_b64 v[4:5], 11, v[4:5]
	s_add_u32 s34, s4, s42
	v_readlane_b32 s4, v254, 48
	v_or_b32_e32 v4, v4, v6
	s_addc_u32 s35, s4, 0
	s_waitcnt vmcnt(0)
	v_lshl_add_u64 v[68:69], s[34:35], 0, v[4:5]
	v_add_u32_e32 v4, s36, v9
	v_ashrrev_i32_e32 v5, 31, v4
	v_lshlrev_b64 v[4:5], 11, v[4:5]
	v_or_b32_e32 v4, v4, v6
	v_lshl_add_u64 v[70:71], s[26:27], 0, v[4:5]
	v_add_u32_e32 v4, s37, v9
	v_subrev_u32_e32 v4, s39, v4
	v_ashrrev_i32_e32 v5, 31, v4
	v_lshlrev_b64 v[4:5], 11, v[4:5]
	v_or_b32_e32 v4, v4, v6
	v_lshl_add_u64 v[72:73], s[34:35], 0, v[4:5]
	v_add_u32_e32 v4, s36, v10
	v_ashrrev_i32_e32 v5, 31, v4
	v_lshlrev_b64 v[4:5], 11, v[4:5]
	v_or_b32_e32 v4, v4, v6
	v_lshl_add_u64 v[74:75], s[26:27], 0, v[4:5]
	v_add_u32_e32 v4, s37, v10
	v_subrev_u32_e32 v4, s39, v4
	v_ashrrev_i32_e32 v5, 31, v4
	v_lshlrev_b64 v[4:5], 11, v[4:5]
	v_or_b32_e32 v4, v4, v6
	v_lshl_add_u64 v[76:77], s[34:35], 0, v[4:5]
	v_add_u32_e32 v4, s36, v11
	v_ashrrev_i32_e32 v5, 31, v4
	v_lshlrev_b64 v[4:5], 11, v[4:5]
	v_or_b32_e32 v4, v4, v6
	v_lshl_add_u64 v[78:79], s[26:27], 0, v[4:5]
	v_add_u32_e32 v4, s37, v11
	v_lshlrev_b32_e32 v1, 4, v1
	v_subrev_u32_e32 v4, s39, v4
	v_or_b32_e32 v83, v1, v0
	v_add_u32_e32 v0, s36, v7
	v_ashrrev_i32_e32 v5, 31, v4
	v_or_b32_e32 v2, v1, v2
	v_ashrrev_i32_e32 v1, 31, v0
	v_lshlrev_b64 v[4:5], 11, v[4:5]
	s_waitcnt vmcnt(0)
; __device__ __forceinline__ void gemm_mainloop_d(const bf16_t* __restrict__ Ap, int lda, const bf16_t* __restrict__ Bt, int K,
;                                                 int m0, int n0, f32x4 (&acc)[4][4], char* lds) {
;     ...
; #pragma unroll
;   for (int m = 0; m < 4; m++)
; #pragma unroll
;     for (int n = 0; n < 4; n++) acc[m][n] = (f32x4){0.f, 0.f, 0.f, 0.f};
;   const int nk = K >> 6;
;   const int lrow = tid >> 3, cph = tid & 7;
;   auto dma = [&](int kt, int st) {
;     char* la = lds + st * 32768; char* lb = la + 16384;
; #pragma unroll
;     for (int i = 0; i < 4; i++) {
;       const int row = i * 32 + lrow; const int c = cph ^ ((row >> 1) & 7);
;       __builtin_amdgcn_global_load_lds((const unsigned*)(Ap + (size_t)(m0 + row) * lda + kt * 64 + c * 8), (__attribute__((address_space(3))) unsigned*)(la + i * 4096 + tid * 16), 16, 0, 0);
;       __builtin_amdgcn_global_load_lds((const unsigned*)(Bt + (size_t)(n0 + row) * K + kt * 64 + c * 8), (__attribute__((address_space(3))) unsigned*)(lb + i * 4096 + tid * 16), 16, 0, 0);
;     }
;   };
;   dma(0, 0);
;   asm volatile("s_waitcnt vmcnt(0)" ::: "memory"); __builtin_amdgcn_s_barrier(); asm volatile("" ::: "memory");
;   for (int kt = 0; kt < nk; kt++) {
;     const int st = kt & 1;
;     if (kt + 1 < nk) dma(kt + 1, st ^ 1);
;     const char* la = lds + st * 32768; const char* lb = la + 16384;
;     bf16x8 af[2][4], bfv[2][4];
; #pragma unroll
;     for (int kc = 0; kc < 2; kc++) {
; #pragma unroll
;       for (int m = 0; m < 4; m++) { const int row = wr * 64 + m * 16 + fr; af[kc][m] = *(const bf16x8*)(la + (row * 8 + ((kc * 4 + fq) ^ ((row >> 1) & 7))) * 16); }
; #pragma unroll
;       for (int n = 0; n < 4; n++) { const int row = wc * 64 + n * 16 + fr; bfv[kc][n] = *(const bf16x8*)(lb + (row * 8 + ((kc * 4 + fq) ^ ((row >> 1) & 7))) * 16); }
;     }
;     __builtin_amdgcn_s_setprio(1);
; #pragma unroll
;     for (int kc = 0; kc < 2; kc++)
; #pragma unroll
;       for (int m = 0; m < 4; m++)
; #pragma unroll
;         for (int n = 0; n < 4; n++) acc[m][n] = __builtin_amdgcn_mfma_f32_16x16x32_bf16(bfv[kc][n], af[kc][m], acc[m][n], 0, 0, 0);
;     __builtin_amdgcn_s_setprio(0);
;     asm volatile("s_waitcnt vmcnt(0) lgkmcnt(0)" ::: "memory"); __builtin_amdgcn_s_barrier(); asm volatile("" ::: "memory");
;   }
	v_lshlrev_b64 v[0:1], 11, v[0:1]
	v_or_b32_e32 v4, v4, v6
	v_or_b32_e32 v0, v0, v6
	v_lshl_add_u64 v[80:81], s[34:35], 0, v[4:5]
	v_mov_b32_e32 v4, 0
	s_mov_b32 s25, 0
	v_lshl_add_u64 v[0:1], s[26:27], 0, v[0:1]
	s_mov_b64 s[26:27], 0
	v_mov_b32_e32 v5, v4
	v_mov_b32_e32 v6, v4
	v_mov_b32_e32 v7, v4
	v_mov_b32_e32 v8, v4
	v_mov_b32_e32 v9, v4
	v_mov_b32_e32 v10, v4
	v_mov_b32_e32 v11, v4
	v_mov_b32_e32 v12, v4
	v_mov_b32_e32 v13, v4
	v_mov_b32_e32 v14, v4
	v_mov_b32_e32 v15, v4
	v_mov_b32_e32 v16, v4
	v_mov_b32_e32 v17, v4
	v_mov_b32_e32 v18, v4
	v_mov_b32_e32 v19, v4
	v_mov_b32_e32 v20, v4
	v_mov_b32_e32 v21, v4
	v_mov_b32_e32 v22, v4
	v_mov_b32_e32 v23, v4
	v_mov_b32_e32 v24, v4
	v_mov_b32_e32 v25, v4
	v_mov_b32_e32 v26, v4
	v_mov_b32_e32 v27, v4
	v_mov_b32_e32 v28, v4
	v_mov_b32_e32 v29, v4
	v_mov_b32_e32 v30, v4
	v_mov_b32_e32 v31, v4
	v_mov_b32_e32 v32, v4
	v_mov_b32_e32 v33, v4
	v_mov_b32_e32 v34, v4
	v_mov_b32_e32 v35, v4
	v_mov_b32_e32 v36, v4
	v_mov_b32_e32 v37, v4
	v_mov_b32_e32 v38, v4
	v_mov_b32_e32 v39, v4
	v_mov_b32_e32 v40, v4
	v_mov_b32_e32 v41, v4
	v_mov_b32_e32 v42, v4
	v_mov_b32_e32 v43, v4
	v_mov_b32_e32 v44, v4
	v_mov_b32_e32 v45, v4
	v_mov_b32_e32 v46, v4
	v_mov_b32_e32 v47, v4
	v_mov_b32_e32 v48, v4
	v_mov_b32_e32 v49, v4
	v_mov_b32_e32 v50, v4
	v_mov_b32_e32 v51, v4
	v_mov_b32_e32 v52, v4
	v_mov_b32_e32 v53, v4
	v_mov_b32_e32 v54, v4
	v_mov_b32_e32 v55, v4
	v_mov_b32_e32 v56, v4
	v_mov_b32_e32 v57, v4
	v_mov_b32_e32 v58, v4
	v_mov_b32_e32 v59, v4
	v_mov_b32_e32 v60, v4
	v_mov_b32_e32 v61, v4
	v_mov_b32_e32 v62, v4
	v_mov_b32_e32 v63, v4
	v_mov_b32_e32 v64, v4
	v_mov_b32_e32 v65, v4
	v_mov_b32_e32 v66, v4
	v_mov_b32_e32 v67, v4
	v_subrev_u32_e32 v150, s46, v0
	v_subrev_u32_e32 v151, s46, v68
	v_subrev_u32_e32 v152, s46, v70
	v_subrev_u32_e32 v153, s46, v72
	v_subrev_u32_e32 v154, s46, v74
	v_subrev_u32_e32 v155, s46, v76
	v_subrev_u32_e32 v156, s46, v78
	v_subrev_u32_e32 v157, s46, v80
	v_readfirstlane_b32 vcc_hi, v82
	s_and_b32 s34, s25, 0x8000
	s_xor_b32 s35, s34, 0x8000
	s_add_i32 s35, s35, vcc_hi
.LBB0_109:
	s_barrier
	s_setprio 3
	s_mov_b32 m0, s35
	s_add_i32 vcc_lo, s35, 0x4000
	global_load_lds_dwordx4 v150, s[46:47]
	s_mov_b32 m0, vcc_lo
	s_add_i32 vcc_lo, s35, 0x1000
	global_load_lds_dwordx4 v151, s[46:47]
	s_mov_b32 m0, vcc_lo
	s_add_i32 vcc_lo, s35, 0x5000
	global_load_lds_dwordx4 v152, s[46:47]
	s_mov_b32 m0, vcc_lo
	s_add_i32 vcc_lo, s35, 0x2000
	global_load_lds_dwordx4 v153, s[46:47]
	s_mov_b32 m0, vcc_lo
	s_add_i32 vcc_lo, s35, 0x6000
	global_load_lds_dwordx4 v154, s[46:47]
	s_mov_b32 m0, vcc_lo
	s_add_i32 vcc_lo, s35, 0x3000
	global_load_lds_dwordx4 v155, s[46:47]
	s_mov_b32 m0, vcc_lo
	s_add_i32 vcc_lo, s35, 0x7000
	global_load_lds_dwordx4 v156, s[46:47]
	s_mov_b32 m0, vcc_lo
	s_nop 0
	global_load_lds_dwordx4 v157, s[46:47]
	v_add_u32_e32 v150, 0x80, v150
	v_add_u32_e32 v151, 0x80, v151
	v_add_u32_e32 v152, 0x80, v152
	v_add_u32_e32 v153, 0x80, v153
	v_add_u32_e32 v154, 0x80, v154
	v_add_u32_e32 v155, 0x80, v155
	v_add_u32_e32 v156, 0x80, v156
	v_add_u32_e32 v157, 0x80, v157
	v_add_u32_e32 v98, s34, v85
	v_add_u32_e32 v114, s34, v84
	v_add_u32_e32 v130, s34, v83
	v_add_u32_e32 v146, s34, v2
	ds_read_b128 v[86:89], v98
	ds_read_b128 v[90:93], v98 offset:2048
	ds_read_b128 v[94:97], v98 offset:4096
	ds_read_b128 v[98:101], v98 offset:6144
	ds_read_b128 v[102:105], v114 offset:16384
	ds_read_b128 v[106:109], v114 offset:18432
	ds_read_b128 v[110:113], v114 offset:20480
	ds_read_b128 v[114:117], v114 offset:22528
	ds_read_b128 v[118:121], v130
	ds_read_b128 v[122:125], v130 offset:2048
	ds_read_b128 v[126:129], v130 offset:4096
	ds_read_b128 v[130:133], v130 offset:6144
	ds_read_b128 v[134:137], v146 offset:16384
	ds_read_b128 v[138:141], v146 offset:18432
	ds_read_b128 v[142:145], v146 offset:20480
	ds_read_b128 v[146:149], v146 offset:22528
	s_setprio 1
	s_waitcnt lgkmcnt(0)
	v_mfma_f32_16x16x32_bf16 v[64:67], v[102:105], v[86:89], v[64:67]
	v_mfma_f32_16x16x32_bf16 v[60:63], v[106:109], v[86:89], v[60:63]
	v_mfma_f32_16x16x32_bf16 v[56:59], v[110:113], v[86:89], v[56:59]
	v_mfma_f32_16x16x32_bf16 v[52:55], v[114:117], v[86:89], v[52:55]
	v_mfma_f32_16x16x32_bf16 v[48:51], v[102:105], v[90:93], v[48:51]
	v_mfma_f32_16x16x32_bf16 v[44:47], v[106:109], v[90:93], v[44:47]
	v_mfma_f32_16x16x32_bf16 v[40:43], v[110:113], v[90:93], v[40:43]
	v_mfma_f32_16x16x32_bf16 v[36:39], v[114:117], v[90:93], v[36:39]
	v_mfma_f32_16x16x32_bf16 v[32:35], v[102:105], v[94:97], v[32:35]
	v_mfma_f32_16x16x32_bf16 v[28:31], v[106:109], v[94:97], v[28:31]
	v_mfma_f32_16x16x32_bf16 v[24:27], v[110:113], v[94:97], v[24:27]
	v_mfma_f32_16x16x32_bf16 v[20:23], v[114:117], v[94:97], v[20:23]
	v_mfma_f32_16x16x32_bf16 v[16:19], v[102:105], v[98:101], v[16:19]
	v_mfma_f32_16x16x32_bf16 v[12:15], v[106:109], v[98:101], v[12:15]
	v_mfma_f32_16x16x32_bf16 v[8:11], v[110:113], v[98:101], v[8:11]
	v_mfma_f32_16x16x32_bf16 v[4:7], v[114:117], v[98:101], v[4:7]
	v_mfma_f32_16x16x32_bf16 v[64:67], v[134:137], v[118:121], v[64:67]
	v_mfma_f32_16x16x32_bf16 v[60:63], v[138:141], v[118:121], v[60:63]
	v_mfma_f32_16x16x32_bf16 v[56:59], v[142:145], v[118:121], v[56:59]
	v_mfma_f32_16x16x32_bf16 v[52:55], v[146:149], v[118:121], v[52:55]
	v_mfma_f32_16x16x32_bf16 v[48:51], v[134:137], v[122:125], v[48:51]
	v_mfma_f32_16x16x32_bf16 v[44:47], v[138:141], v[122:125], v[44:47]
	v_mfma_f32_16x16x32_bf16 v[40:43], v[142:145], v[122:125], v[40:43]
	v_mfma_f32_16x16x32_bf16 v[36:39], v[146:149], v[122:125], v[36:39]
	v_mfma_f32_16x16x32_bf16 v[32:35], v[134:137], v[126:129], v[32:35]
	v_mfma_f32_16x16x32_bf16 v[28:31], v[138:141], v[126:129], v[28:31]
	v_mfma_f32_16x16x32_bf16 v[24:27], v[142:145], v[126:129], v[24:27]
	v_mfma_f32_16x16x32_bf16 v[20:23], v[146:149], v[126:129], v[20:23]
	v_mfma_f32_16x16x32_bf16 v[16:19], v[134:137], v[130:133], v[16:19]
	v_mfma_f32_16x16x32_bf16 v[12:15], v[138:141], v[130:133], v[12:15]
	v_mfma_f32_16x16x32_bf16 v[8:11], v[142:145], v[130:133], v[8:11]
	v_mfma_f32_16x16x32_bf16 v[4:7], v[146:149], v[130:133], v[4:7]
	s_setprio 0
	s_waitcnt vmcnt(0) lgkmcnt(0)
	s_add_u32 s26, s26, 0x80
	s_addc_u32 s27, s27, 0
	s_add_i32 s25, s25, 0x8000
	s_and_b32 s34, s25, 0x8000
	s_xor_b32 s35, s34, 0x8000
	s_add_i32 s35, s35, vcc_hi
	s_cmpk_lg_i32 s26, 0x780
	s_cbranch_scc1 .LBB0_109
; __device__ __forceinline__ unsigned char* WS(const Params& p) { unsigned z = 0; asm volatile("" : "+s"(z)); return p.ws + z; }
; __device__ __forceinline__ void gemm_mainloop_d(const bf16_t* __restrict__ Ap, int lda, const bf16_t* __restrict__ Bt, int K,
;                                                 int m0, int n0, f32x4 (&acc)[4][4], char* lds) {
;     ...
;     const char* la = lds + st * 32768; const char* lb = la + 16384;
;     bf16x8 af[2][4], bfv[2][4];
; #pragma unroll
;     for (int kc = 0; kc < 2; kc++) {
; #pragma unroll
;       for (int m = 0; m < 4; m++) { const int row = wr * 64 + m * 16 + fr; af[kc][m] = *(const bf16x8*)(la + (row * 8 + ((kc * 4 + fq) ^ ((row >> 1) & 7))) * 16); }
; #pragma unroll
;       for (int n = 0; n < 4; n++) { const int row = wc * 64 + n * 16 + fr; bfv[kc][n] = *(const bf16x8*)(lb + (row * 8 + ((kc * 4 + fq) ^ ((row >> 1) & 7))) * 16); }
;     }
;     __builtin_amdgcn_s_setprio(1);
; #pragma unroll
;     for (int kc = 0; kc < 2; kc++)
; #pragma unroll
;       for (int m = 0; m < 4; m++)
; #pragma unroll
;         for (int n = 0; n < 4; n++) acc[m][n] = __builtin_amdgcn_mfma_f32_16x16x32_bf16(bfv[kc][n], af[kc][m], acc[m][n], 0, 0, 0);
;     __builtin_amdgcn_s_setprio(0);
;     asm volatile("s_waitcnt vmcnt(0) lgkmcnt(0)" ::: "memory"); __builtin_amdgcn_s_barrier(); asm volatile("" ::: "memory");
; __device__ __forceinline__ void gemm_GU(const Params& p, int item, char* lds) {
;     ...
;   GEMM_IDS
;   const float* rssg = (const float*)(WS(p) + OFF_RSS) + T + m0;
;   bf16_t* U = (bf16_t*)(WS(p) + OFF_U);
; #pragma unroll
;   for (int m = 0; m < 4; m++) {
;     const int rl = wr * 64 + m * 16 + fr; const float r = rsqrtf(rssg[rl] * (1.f / 1024.f) + 1e-6f);
	s_barrier
	v_add_u32_e32 v0, 0, v85
	ds_read_b128 v[68:71], v0 offset:32768
	ds_read_b128 v[72:75], v0 offset:34816
	ds_read_b128 v[76:79], v0 offset:36864
	ds_read_b128 v[86:89], v0 offset:38912
	v_add_u32_e32 v0, 0, v84
	ds_read_b128 v[90:93], v0 offset:49152
	ds_read_b128 v[94:97], v0 offset:51200
	ds_read_b128 v[98:101], v0 offset:53248
	ds_read_b128 v[102:105], v0 offset:55296
	v_add_u32_e32 v0, 0, v83
	ds_read_b128 v[80:83], v0 offset:32768
	ds_read_b128 v[106:109], v0 offset:34816
	ds_read_b128 v[110:113], v0 offset:36864
	ds_read_b128 v[114:117], v0 offset:38912
	v_add_u32_e32 v0, 0, v2
	ds_read_b128 v[118:121], v0 offset:49152
	ds_read_b128 v[122:125], v0 offset:51200
	ds_read_b128 v[126:129], v0 offset:53248
	ds_read_b128 v[130:133], v0 offset:55296
	s_setprio 1
	s_waitcnt lgkmcnt(0)
	v_mfma_f32_16x16x32_bf16 v[64:67], v[90:93], v[68:71], v[64:67]
	v_mfma_f32_16x16x32_bf16 v[60:63], v[94:97], v[68:71], v[60:63]
	v_mfma_f32_16x16x32_bf16 v[56:59], v[98:101], v[68:71], v[56:59]
	v_mfma_f32_16x16x32_bf16 v[52:55], v[102:105], v[68:71], v[52:55]
	v_mfma_f32_16x16x32_bf16 v[48:51], v[90:93], v[72:75], v[48:51]
	v_mfma_f32_16x16x32_bf16 v[44:47], v[94:97], v[72:75], v[44:47]
	v_mfma_f32_16x16x32_bf16 v[68:71], v[98:101], v[72:75], v[40:43]
	v_mfma_f32_16x16x32_bf16 v[72:75], v[102:105], v[72:75], v[36:39]
	v_mfma_f32_16x16x32_bf16 v[32:35], v[90:93], v[76:79], v[32:35]
	v_mfma_f32_16x16x32_bf16 v[28:31], v[94:97], v[76:79], v[28:31]
	v_mfma_f32_16x16x32_bf16 v[134:137], v[98:101], v[76:79], v[24:27]
	v_mfma_f32_16x16x32_bf16 v[76:79], v[102:105], v[76:79], v[20:23]
	v_mfma_f32_16x16x32_bf16 v[16:19], v[90:93], v[86:89], v[16:19]
	v_mfma_f32_16x16x32_bf16 v[12:15], v[94:97], v[86:89], v[12:15]
	v_mfma_f32_16x16x32_bf16 v[90:93], v[98:101], v[86:89], v[8:11]
	v_mfma_f32_16x16x32_bf16 v[84:87], v[102:105], v[86:89], v[4:7]
	v_mfma_f32_16x16x32_bf16 v[64:67], v[118:121], v[80:83], v[64:67]
	v_mfma_f32_16x16x32_bf16 v[60:63], v[122:125], v[80:83], v[60:63]
	v_mfma_f32_16x16x32_bf16 v[56:59], v[126:129], v[80:83], v[56:59]
	v_mfma_f32_16x16x32_bf16 v[52:55], v[130:133], v[80:83], v[52:55]
	v_mfma_f32_16x16x32_bf16 v[40:43], v[118:121], v[106:109], v[48:51]
	v_mfma_f32_16x16x32_bf16 v[48:51], v[122:125], v[106:109], v[44:47]
	v_mfma_f32_16x16x32_bf16 v[36:39], v[126:129], v[106:109], v[68:71]
	v_mfma_f32_16x16x32_bf16 v[44:47], v[130:133], v[106:109], v[72:75]
	v_mfma_f32_16x16x32_bf16 v[24:27], v[118:121], v[110:113], v[32:35]
	v_mfma_f32_16x16x32_bf16 v[32:35], v[122:125], v[110:113], v[28:31]
	v_mfma_f32_16x16x32_bf16 v[20:23], v[126:129], v[110:113], v[134:137]
	v_mfma_f32_16x16x32_bf16 v[28:31], v[130:133], v[110:113], v[76:79]
	v_mfma_f32_16x16x32_bf16 v[8:11], v[118:121], v[114:117], v[16:19]
	v_mfma_f32_16x16x32_bf16 v[16:19], v[122:125], v[114:117], v[12:15]
	v_mfma_f32_16x16x32_bf16 v[4:7], v[126:129], v[114:117], v[90:93]
	v_mfma_f32_16x16x32_bf16 v[12:15], v[130:133], v[114:117], v[84:87]
	s_setprio 0
	v_mov_b32_e32 v2, v198
	s_mov_b32 s25, s89
	s_waitcnt vmcnt(0) lgkmcnt(0)
	s_barrier
	s_add_u32 s34, s46, s25
	s_addc_u32 s35, s47, 0
	s_ashr_i32 s25, s24, 31
	v_and_b32_e32 v0, 15, v2
	s_lshl_b64 s[26:27], s[24:25], 2
	v_ashrrev_i32_e32 v1, 1, v2
	s_movk_i32 s4, 0xffc0
	s_add_u32 s26, s34, s26
	v_and_or_b32 v0, v1, s4, v0
	s_addc_u32 s27, s35, s27
	v_ashrrev_i32_e32 v1, 31, v0
	v_lshl_add_u64 v[68:69], v[0:1], 2, s[26:27]
	s_mov_b32 s26, 0xff9c000
	v_add_co_u32_e32 v70, vcc, s26, v68
	s_mov_b32 s25, s89
	s_nop 0
	v_addc_co_u32_e32 v71, vcc, 0, v69, vcc
	global_load_dword v74, v[70:71], off
	v_mov_b32_e32 v71, v64
	v_mov_b32_e32 v64, v61
	v_mov_b32_e32 v61, v66
	v_mov_b32_e32 v66, v63
	v_mov_b32_e32 v63, v56
	v_mov_b32_e32 v56, v53
	v_mov_b32_e32 v70, v60
	v_mov_b32_e32 v60, v62
	v_mov_b32_e32 v62, v52
	v_mov_b32_e32 v72, v54
	v_mov_b32_e32 v73, v58
	v_mov_b32_e32 v58, v55
	v_lshrrev_b32_e32 v1, 1, v2
	v_lshrrev_b32_e32 v2, 2, v2
	s_add_u32 s26, s46, s25
	v_and_b32_e32 v52, 12, v2
	v_add_u32_e32 v2, s24, v0
	s_addc_u32 s27, s47, 0
	s_mov_b64 s[24:25], 0xff9c000
	v_lshl_add_u64 v[54:55], v[68:69], 0, s[24:25]
	s_add_u32 s24, s26, 0x768000
	v_and_b32_e32 v1, 32, v1
	s_addc_u32 s25, s27, 0
	s_ashr_i32 s26, s31, 1
	v_or3_b32 v52, v1, s26, v52
	v_mov_b64_e32 v[0:1], s[24:25]
	v_mad_i64_i32 v[68:69], s[24:25], v2, s33, v[0:1]
	s_add_i32 s30, s30, s77
	s_add_i32 s29, s29, s2
	s_add_i32 s28, s28, s3
	s_cmpk_gt_i32 s30, 0x15ff
	s_waitcnt vmcnt(0)
; __device__ __forceinline__ unsigned pk2(float lo, float hi) { unsigned r; asm("v_cvt_pk_bf16_f32 %0, %1, %2" : "=v"(r) : "v"(lo), "v"(hi)); return r; }
; __device__ __forceinline__ float sigmoidf_(float x) { return __builtin_amdgcn_rcpf(1.0f + __expf(-x)); }
; __device__ __forceinline__ void gemm_GU(const Params& p, int item, char* lds) {
;     ...
; #pragma unroll
;   for (int m = 0; m < 4; m++) {
;     const int rl = wr * 64 + m * 16 + fr; const float r = rsqrtf(rssg[rl] * (1.f / 1024.f) + 1e-6f);
; #pragma unroll
;     for (int i = 0; i < 2; i++) {
;       f32x4 g = acc[m][2 * i] * r, u = acc[m][2 * i + 1] * r, o;
; #pragma unroll
;       for (int j = 0; j < 4; j++) o[j] = g[j] * sigmoidf_(g[j]) * u[j];
;       const int col = (n0 >> 1) + wc * 32 + i * 16 + fq * 4;
;       u32x2 w; w[0] = pk2(o[0], o[1]); w[1] = pk2(o[2], o[3]);
;       *(u32x2*)(U + (size_t)(m0 + rl) * DFF + col) = w;
;     }
	v_fmamk_f32 v53, v74, 0x3a800000, v200
	v_mul_f32_e32 v74, 0x4b800000, v53
	v_cmp_gt_f32_e32 vcc, s83, v53
	s_nop 1
	v_cndmask_b32_e32 v53, v53, v74, vcc
	v_rsq_f32_e32 v74, v53
	v_ashrrev_i32_e32 v53, 31, v52
	v_lshlrev_b64 v[52:53], 1, v[52:53]
	v_lshl_add_u64 v[68:69], v[68:69], 0, v[52:53]
	v_mul_f32_e32 v75, 0x45800000, v74
	v_cndmask_b32_e32 v74, v74, v75, vcc
	v_pk_mul_f32 v[60:61], v[60:61], v[74:75] op_sel_hi:[1,0]
	v_pk_mul_f32 v[70:71], v[70:71], v[74:75] op_sel_hi:[1,0]
	v_pk_mul_f32 v[64:65], v[64:65], v[74:75] op_sel_hi:[1,0]
	v_pk_mul_f32 v[66:67], v[66:67], v[74:75] op_sel_hi:[1,0]
	v_mul_f32_e32 v76, 0xbfb8aa3b, v61
	v_pk_mul_f32 v[62:63], v[62:63], v[74:75] op_sel_hi:[1,0]
	v_pk_mul_f32 v[56:57], v[56:57], v[74:75] op_sel_hi:[1,0]
	v_pk_mul_f32 v[72:73], v[72:73], v[74:75] op_sel_hi:[1,0]
	v_pk_mul_f32 v[58:59], v[58:59], v[74:75] op_sel_hi:[1,0]
	v_mul_f32_e32 v74, 0xbfb8aa3b, v71
	v_mul_f32_e32 v75, 0xbfb8aa3b, v65
	v_mul_f32_e32 v77, 0xbfb8aa3b, v67
	v_exp_f32_e32 v76, v76
	v_exp_f32_e32 v74, v74
	v_exp_f32_e32 v75, v75
	v_exp_f32_e32 v77, v77
	v_add_f32_e32 v76, 1.0, v76
	v_mul_f32_e32 v79, 0xbfb8aa3b, v57
	v_add_f32_e32 v74, 1.0, v74
	v_add_f32_e32 v75, 1.0, v75
	v_add_f32_e32 v77, 1.0, v77
	v_rcp_f32_e32 v76, v76
	v_mul_f32_e32 v80, 0xbfb8aa3b, v73
	v_exp_f32_e32 v79, v79
	v_rcp_f32_e32 v74, v74
	v_rcp_f32_e32 v75, v75
	v_rcp_f32_e32 v77, v77
	v_mul_f32_e32 v78, 0xbfb8aa3b, v63
	v_mul_f32_e32 v81, 0xbfb8aa3b, v59
	v_exp_f32_e32 v80, v80
	v_exp_f32_e32 v78, v78
	v_exp_f32_e32 v81, v81
	v_mul_f32_e32 v61, v61, v76
	v_add_f32_e32 v79, 1.0, v79
	v_mul_f32_e32 v71, v71, v74
	v_mul_f32_e32 v65, v65, v75
	v_mul_f32_e32 v67, v67, v77
	v_mul_f32_e32 v61, v60, v61
	v_add_f32_e32 v80, 1.0, v80
	v_rcp_f32_e32 v79, v79
	v_mul_f32_e32 v70, v70, v71
	v_mul_f32_e32 v64, v64, v65
	v_mul_f32_e32 v65, v66, v67
	v_cvt_pk_bf16_f32 v60, v70, v64
	v_cvt_pk_bf16_f32 v61, v61, v65
	v_add_f32_e32 v78, 1.0, v78
	global_store_dwordx2 v[68:69], v[60:61], off
	v_rcp_f32_e32 v60, v80
	v_add_f32_e32 v61, 1.0, v81
	v_rcp_f32_e32 v78, v78
	v_rcp_f32_e32 v61, v61
	v_mul_f32_e32 v57, v57, v79
	v_mul_f32_e32 v56, v56, v57
	v_mul_f32_e32 v57, v73, v60
	v_mul_f32_e32 v63, v63, v78
	v_mul_f32_e32 v57, v72, v57
	v_mul_f32_e32 v59, v59, v61
	v_mul_f32_e32 v62, v62, v63
	v_mul_f32_e32 v58, v58, v59
	v_cvt_pk_bf16_f32 v56, v62, v56
	v_cvt_pk_bf16_f32 v57, v57, v58
	global_store_dwordx2 v[68:69], v[56:57], off offset:32
	global_load_dword v58, v[54:55], off offset:64
	v_mov_b32_e32 v57, v40
	v_mov_b32_e32 v40, v49
	v_mov_b32_e32 v49, v42
	v_mov_b32_e32 v42, v51
	v_mov_b32_e32 v51, v36
	v_mov_b32_e32 v36, v45
	v_mov_b32_e32 v45, v38
	v_mov_b32_e32 v38, v47
	v_mov_b32_e32 v56, v48
	v_mov_b32_e32 v48, v50
	v_mov_b32_e32 v50, v44
	v_mov_b32_e32 v44, v46
	v_add_u32_e32 v46, 16, v2
	s_waitcnt vmcnt(0)
	v_fmamk_f32 v47, v58, 0x3a800000, v200
	v_mul_f32_e32 v58, 0x4b800000, v47
	v_cmp_gt_f32_e32 vcc, s83, v47
	s_nop 1
	v_cndmask_b32_e32 v47, v47, v58, vcc
	v_rsq_f32_e32 v58, v47
	v_mad_i64_i32 v[46:47], s[24:25], v46, s33, v[0:1]
	v_lshl_add_u64 v[46:47], v[46:47], 0, v[52:53]
	v_mul_f32_e32 v59, 0x45800000, v58
	v_cndmask_b32_e32 v58, v58, v59, vcc
	v_pk_mul_f32 v[56:57], v[56:57], v[58:59] op_sel_hi:[1,0]
	v_pk_mul_f32 v[40:41], v[40:41], v[58:59] op_sel_hi:[1,0]
	v_pk_mul_f32 v[48:49], v[48:49], v[58:59] op_sel_hi:[1,0]
	v_pk_mul_f32 v[42:43], v[42:43], v[58:59] op_sel_hi:[1,0]
	v_pk_mul_f32 v[36:37], v[36:37], v[58:59] op_sel_hi:[1,0]
	v_pk_mul_f32 v[38:39], v[38:39], v[58:59] op_sel_hi:[1,0]
	v_pk_mul_f32 v[50:51], v[50:51], v[58:59] op_sel_hi:[1,0]
	v_pk_mul_f32 v[44:45], v[44:45], v[58:59] op_sel_hi:[1,0]
	v_mul_f32_e32 v58, 0xbfb8aa3b, v57
	v_mul_f32_e32 v59, 0xbfb8aa3b, v41
	v_mul_f32_e32 v60, 0xbfb8aa3b, v49
	v_mul_f32_e32 v61, 0xbfb8aa3b, v43
	v_mul_f32_e32 v63, 0xbfb8aa3b, v37
	v_mul_f32_e32 v65, 0xbfb8aa3b, v39
	v_mul_f32_e32 v62, 0xbfb8aa3b, v51
	v_mul_f32_e32 v64, 0xbfb8aa3b, v45
	v_exp_f32_e32 v58, v58
	v_exp_f32_e32 v59, v59
	v_exp_f32_e32 v60, v60
	v_exp_f32_e32 v61, v61
	v_exp_f32_e32 v63, v63
	v_exp_f32_e32 v65, v65
	v_exp_f32_e32 v62, v62
	v_exp_f32_e32 v64, v64
	v_add_f32_e32 v58, 1.0, v58
	v_add_f32_e32 v59, 1.0, v59
	v_add_f32_e32 v60, 1.0, v60
	v_add_f32_e32 v61, 1.0, v61
	v_add_f32_e32 v63, 1.0, v63
	v_add_f32_e32 v65, 1.0, v65
	v_add_f32_e32 v62, 1.0, v62
	v_add_f32_e32 v64, 1.0, v64
	v_rcp_f32_e32 v58, v58
	v_rcp_f32_e32 v59, v59
	v_rcp_f32_e32 v60, v60
	v_rcp_f32_e32 v61, v61
	v_rcp_f32_e32 v63, v63
	v_rcp_f32_e32 v65, v65
	v_rcp_f32_e32 v62, v62
	v_rcp_f32_e32 v64, v64
	v_mul_f32_e32 v57, v57, v58
	v_mul_f32_e32 v41, v41, v59
	v_mul_f32_e32 v49, v49, v60
	v_mul_f32_e32 v43, v43, v61
	v_mul_f32_e32 v37, v37, v63
	v_mul_f32_e32 v39, v39, v65
	v_mul_f32_e32 v51, v51, v62
	v_mul_f32_e32 v45, v45, v64
	v_mul_f32_e32 v56, v56, v57
	v_mul_f32_e32 v40, v40, v41
	v_mul_f32_e32 v41, v48, v49
	v_mul_f32_e32 v42, v42, v43
	v_mul_f32_e32 v48, v36, v37
	v_mul_f32_e32 v39, v38, v39
	v_cvt_pk_bf16_f32 v36, v56, v40
	v_cvt_pk_bf16_f32 v37, v41, v42
	v_mul_f32_e32 v43, v50, v51
	v_mul_f32_e32 v44, v44, v45
	v_cvt_pk_bf16_f32 v38, v43, v48
	v_cvt_pk_bf16_f32 v39, v44, v39
	global_store_dwordx2 v[46:47], v[36:37], off
	global_store_dwordx2 v[46:47], v[38:39], off offset:32
	global_load_dword v38, v[54:55], off offset:128
	v_mov_b32_e32 v37, v24
	v_mov_b32_e32 v24, v33
	v_mov_b32_e32 v33, v26
	v_mov_b32_e32 v26, v35
	v_mov_b32_e32 v35, v20
	v_mov_b32_e32 v20, v29
	v_mov_b32_e32 v29, v22
	v_mov_b32_e32 v22, v31
	v_mov_b32_e32 v36, v32
	v_mov_b32_e32 v32, v34
	v_mov_b32_e32 v34, v28
	v_mov_b32_e32 v28, v30
	v_add_u32_e32 v30, 32, v2
	v_add_u32_e32 v2, 48, v2
	s_waitcnt vmcnt(0)
; __device__ __forceinline__ unsigned pk2(float lo, float hi) { unsigned r; asm("v_cvt_pk_bf16_f32 %0, %1, %2" : "=v"(r) : "v"(lo), "v"(hi)); return r; }
; __device__ __forceinline__ float sigmoidf_(float x) { return __builtin_amdgcn_rcpf(1.0f + __expf(-x)); }
; __device__ __forceinline__ void gemm_GU(const Params& p, int item, char* lds) {
;     ...
; #pragma unroll
;   for (int m = 0; m < 4; m++) {
;     const int rl = wr * 64 + m * 16 + fr; const float r = rsqrtf(rssg[rl] * (1.f / 1024.f) + 1e-6f);
; #pragma unroll
;     for (int i = 0; i < 2; i++) {
;       f32x4 g = acc[m][2 * i] * r, u = acc[m][2 * i + 1] * r, o;
; #pragma unroll
;       for (int j = 0; j < 4; j++) o[j] = g[j] * sigmoidf_(g[j]) * u[j];
;       const int col = (n0 >> 1) + wc * 32 + i * 16 + fq * 4;
;       u32x2 w; w[0] = pk2(o[0], o[1]); w[1] = pk2(o[2], o[3]);
;       *(u32x2*)(U + (size_t)(m0 + rl) * DFF + col) = w;
;     }
;   }
;   __syncthreads();
	v_fmamk_f32 v31, v38, 0x3a800000, v200
	v_mul_f32_e32 v38, 0x4b800000, v31
	v_cmp_gt_f32_e32 vcc, s83, v31
	s_nop 1
	v_cndmask_b32_e32 v31, v31, v38, vcc
	v_rsq_f32_e32 v38, v31
	v_mad_i64_i32 v[30:31], s[24:25], v30, s33, v[0:1]
	v_lshl_add_u64 v[30:31], v[30:31], 0, v[52:53]
	v_mul_f32_e32 v39, 0x45800000, v38
	v_cndmask_b32_e32 v38, v38, v39, vcc
	v_pk_mul_f32 v[36:37], v[36:37], v[38:39] op_sel_hi:[1,0]
	v_pk_mul_f32 v[24:25], v[24:25], v[38:39] op_sel_hi:[1,0]
	v_pk_mul_f32 v[32:33], v[32:33], v[38:39] op_sel_hi:[1,0]
	v_pk_mul_f32 v[26:27], v[26:27], v[38:39] op_sel_hi:[1,0]
	v_pk_mul_f32 v[20:21], v[20:21], v[38:39] op_sel_hi:[1,0]
	v_pk_mul_f32 v[22:23], v[22:23], v[38:39] op_sel_hi:[1,0]
	v_pk_mul_f32 v[34:35], v[34:35], v[38:39] op_sel_hi:[1,0]
	v_pk_mul_f32 v[28:29], v[28:29], v[38:39] op_sel_hi:[1,0]
	v_mul_f32_e32 v38, 0xbfb8aa3b, v37
	v_mul_f32_e32 v39, 0xbfb8aa3b, v25
	v_mul_f32_e32 v40, 0xbfb8aa3b, v33
	v_mul_f32_e32 v41, 0xbfb8aa3b, v27
	v_mul_f32_e32 v43, 0xbfb8aa3b, v21
	v_mul_f32_e32 v45, 0xbfb8aa3b, v23
	v_mul_f32_e32 v42, 0xbfb8aa3b, v35
	v_mul_f32_e32 v44, 0xbfb8aa3b, v29
	v_exp_f32_e32 v38, v38
	v_exp_f32_e32 v39, v39
	v_exp_f32_e32 v40, v40
	v_exp_f32_e32 v41, v41
	v_exp_f32_e32 v43, v43
	v_exp_f32_e32 v45, v45
	v_exp_f32_e32 v42, v42
	v_exp_f32_e32 v44, v44
	v_add_f32_e32 v38, 1.0, v38
	v_add_f32_e32 v39, 1.0, v39
	v_add_f32_e32 v40, 1.0, v40
	v_add_f32_e32 v41, 1.0, v41
	v_add_f32_e32 v43, 1.0, v43
	v_add_f32_e32 v45, 1.0, v45
	v_add_f32_e32 v42, 1.0, v42
	v_add_f32_e32 v44, 1.0, v44
	v_rcp_f32_e32 v38, v38
	v_rcp_f32_e32 v39, v39
	v_rcp_f32_e32 v40, v40
	v_rcp_f32_e32 v41, v41
	v_rcp_f32_e32 v43, v43
	v_rcp_f32_e32 v45, v45
	v_rcp_f32_e32 v42, v42
	v_rcp_f32_e32 v44, v44
	v_mul_f32_e32 v37, v37, v38
	v_mul_f32_e32 v25, v25, v39
	v_mul_f32_e32 v33, v33, v40
	v_mul_f32_e32 v27, v27, v41
	v_mul_f32_e32 v21, v21, v43
	v_mul_f32_e32 v23, v23, v45
	v_mul_f32_e32 v35, v35, v42
	v_mul_f32_e32 v29, v29, v44
	v_mul_f32_e32 v36, v36, v37
	v_mul_f32_e32 v24, v24, v25
	v_mul_f32_e32 v25, v32, v33
	v_mul_f32_e32 v26, v26, v27
	v_mul_f32_e32 v32, v20, v21
	v_mul_f32_e32 v23, v22, v23
	v_cvt_pk_bf16_f32 v20, v36, v24
	v_cvt_pk_bf16_f32 v21, v25, v26
	v_mul_f32_e32 v27, v34, v35
	v_mul_f32_e32 v28, v28, v29
	v_cvt_pk_bf16_f32 v22, v27, v32
	v_cvt_pk_bf16_f32 v23, v28, v23
	global_store_dwordx2 v[30:31], v[20:21], off
	global_store_dwordx2 v[30:31], v[22:23], off offset:32
	global_load_dword v22, v[54:55], off offset:192
	v_mov_b32_e32 v20, v16
	v_mov_b32_e32 v16, v18
	v_mov_b32_e32 v18, v12
	v_mov_b32_e32 v12, v14
	v_mov_b32_e32 v21, v8
	v_mov_b32_e32 v8, v17
	v_mov_b32_e32 v17, v10
	v_mov_b32_e32 v10, v19
	v_mov_b32_e32 v19, v4
	v_mov_b32_e32 v4, v13
	v_mov_b32_e32 v13, v6
	v_mov_b32_e32 v6, v15
	v_mad_i64_i32 v[0:1], s[24:25], v2, s33, v[0:1]
	v_lshl_add_u64 v[0:1], v[0:1], 0, v[52:53]
	s_waitcnt vmcnt(0)
	v_fmamk_f32 v14, v22, 0x3a800000, v200
	v_mul_f32_e32 v15, 0x4b800000, v14
	v_cmp_gt_f32_e32 vcc, s83, v14
	s_nop 1
	v_cndmask_b32_e32 v14, v14, v15, vcc
	v_rsq_f32_e32 v14, v14
	s_nop 0
	v_mul_f32_e32 v2, 0x45800000, v14
	v_cndmask_b32_e32 v2, v14, v2, vcc
	v_pk_mul_f32 v[14:15], v[20:21], v[2:3] op_sel_hi:[1,0]
	v_pk_mul_f32 v[8:9], v[8:9], v[2:3] op_sel_hi:[1,0]
	v_pk_mul_f32 v[16:17], v[16:17], v[2:3] op_sel_hi:[1,0]
	v_pk_mul_f32 v[10:11], v[10:11], v[2:3] op_sel_hi:[1,0]
	v_pk_mul_f32 v[4:5], v[4:5], v[2:3] op_sel_hi:[1,0]
	v_pk_mul_f32 v[6:7], v[6:7], v[2:3] op_sel_hi:[1,0]
	v_pk_mul_f32 v[18:19], v[18:19], v[2:3] op_sel_hi:[1,0]
	v_pk_mul_f32 v[12:13], v[12:13], v[2:3] op_sel_hi:[1,0]
	v_mul_f32_e32 v2, 0xbfb8aa3b, v15
	v_mul_f32_e32 v20, 0xbfb8aa3b, v9
	v_mul_f32_e32 v21, 0xbfb8aa3b, v17
	v_mul_f32_e32 v22, 0xbfb8aa3b, v11
	v_mul_f32_e32 v24, 0xbfb8aa3b, v5
	v_mul_f32_e32 v26, 0xbfb8aa3b, v7
	v_mul_f32_e32 v23, 0xbfb8aa3b, v19
	v_mul_f32_e32 v25, 0xbfb8aa3b, v13
	v_exp_f32_e32 v2, v2
	v_exp_f32_e32 v20, v20
	v_exp_f32_e32 v21, v21
	v_exp_f32_e32 v22, v22
	v_exp_f32_e32 v24, v24
	v_exp_f32_e32 v26, v26
	v_exp_f32_e32 v23, v23
	v_exp_f32_e32 v25, v25
	v_add_f32_e32 v2, 1.0, v2
	v_add_f32_e32 v20, 1.0, v20
	v_add_f32_e32 v21, 1.0, v21
	v_add_f32_e32 v22, 1.0, v22
	v_add_f32_e32 v24, 1.0, v24
	v_add_f32_e32 v26, 1.0, v26
	v_add_f32_e32 v23, 1.0, v23
	v_add_f32_e32 v25, 1.0, v25
	v_rcp_f32_e32 v2, v2
	v_rcp_f32_e32 v20, v20
	v_rcp_f32_e32 v21, v21
	v_rcp_f32_e32 v22, v22
	v_rcp_f32_e32 v24, v24
	v_rcp_f32_e32 v26, v26
	v_rcp_f32_e32 v23, v23
	v_rcp_f32_e32 v25, v25
	v_mul_f32_e32 v2, v15, v2
	v_mul_f32_e32 v9, v9, v20
	v_mul_f32_e32 v15, v17, v21
	v_mul_f32_e32 v11, v11, v22
	v_mul_f32_e32 v5, v5, v24
	v_mul_f32_e32 v7, v7, v26
	v_mul_f32_e32 v17, v19, v23
	v_mul_f32_e32 v13, v13, v25
	v_mul_f32_e32 v2, v14, v2
	v_mul_f32_e32 v8, v8, v9
	v_mul_f32_e32 v9, v16, v15
	v_mul_f32_e32 v10, v10, v11
	v_mul_f32_e32 v14, v4, v5
	v_mul_f32_e32 v7, v6, v7
	v_cvt_pk_bf16_f32 v4, v2, v8
	v_cvt_pk_bf16_f32 v5, v9, v10
	v_mul_f32_e32 v11, v18, v17
	v_mul_f32_e32 v12, v12, v13
	v_cvt_pk_bf16_f32 v6, v11, v14
	v_cvt_pk_bf16_f32 v7, v12, v7
	global_store_dwordx2 v[0:1], v[4:5], off
	global_store_dwordx2 v[0:1], v[6:7], off offset:32
	s_barrier
	s_cbranch_scc0 .LBB0_108

; __device__ __forceinline__ int opaque_tid() { int t = threadIdx.x; asm volatile("" : "+v"(t)); return t; }
; __device__ __forceinline__ void gemm_mainloop_d(const bf16_t* __restrict__ Ap, int lda, const bf16_t* __restrict__ Bt, int K,
;                                                 int m0, int n0, f32x4 (&acc)[4][4], char* lds) {
;   const int tid = opaque_tid(), lane = tid & 63, wid = tid >> 6, wr = wid >> 1, wc = wid & 1, fr = lane & 15, fq = lane >> 4;
; #pragma unroll
;   for (int m = 0; m < 4; m++)
; #pragma unroll
;     for (int n = 0; n < 4; n++) acc[m][n] = (f32x4){0.f, 0.f, 0.f, 0.f};
;   const int nk = K >> 6;
;   const int lrow = tid >> 3, cph = tid & 7;
;   auto dma = [&](int kt, int st) {
;     char* la = lds + st * 32768; char* lb = la + 16384;
; #pragma unroll
;     for (int i = 0; i < 4; i++) {
;       const int row = i * 32 + lrow; const int c = cph ^ ((row >> 1) & 7);
;       __builtin_amdgcn_global_load_lds((const unsigned*)(Ap + (size_t)(m0 + row) * lda + kt * 64 + c * 8), (__attribute__((address_space(3))) unsigned*)(la + i * 4096 + tid * 16), 16, 0, 0);
;       __builtin_amdgcn_global_load_lds((const unsigned*)(Bt + (size_t)(n0 + row) * K + kt * 64 + c * 8), (__attribute__((address_space(3))) unsigned*)(lb + i * 4096 + tid * 16), 16, 0, 0);
;     }
;   };
;   dma(0, 0);
;   asm volatile("s_waitcnt vmcnt(0)" ::: "memory"); __builtin_amdgcn_s_barrier(); asm volatile("" ::: "memory");
.LBB0_125:
	s_and_b32 s43, s41, 0xffffff80
	s_and_b32 s37, s40, 0x380
	s_mov_b32 s44, 0
	s_add_u32 s2, s46, s44
	s_addc_u32 s3, s47, 0
	s_add_u32 s30, s2, 0xc0a8000
	s_addc_u32 s31, s3, 0
	s_mov_b32 s35, 0
	s_mov_b32 s36, 0
	s_lshl_b32 s2, s42, 4
	v_mov_b32_e32 v4, v198
	s_and_b32 s3, s2, 0xffffff80
	s_lshl_b32 s2, s42, 7
	v_ashrrev_i32_e32 v7, 3, v4
	v_lshrrev_b32_e32 v8, 1, v7
	v_add_u32_e32 v0, s3, v7
	v_xor_b32_e32 v2, v8, v4
	v_ashrrev_i32_e32 v1, 31, v0
	v_lshlrev_b64 v[0:1], 11, v[0:1]
	v_lshlrev_b32_e32 v2, 4, v2
	v_lshl_add_u32 v82, v4, 4, 0
	v_lshl_add_u64 v[0:1], s[30:31], 0, v[0:1]
	v_and_b32_e32 v2, 0x70, v2
	v_readfirstlane_b32 s45, v82
	s_and_b32 s2, s2, 0x380
	v_lshl_add_u64 v[0:1], v[0:1], 0, v[2:3]
	s_mov_b32 m0, s45
	v_add_u32_e32 v9, 0x4000, v82
	global_load_lds_dwordx4 v[0:1], off
	v_add_u32_e32 v0, s2, v7
	v_ashrrev_i32_e32 v1, 31, v0
	v_lshlrev_b64 v[0:1], 11, v[0:1]
	v_lshl_add_u64 v[0:1], s[24:25], 0, v[0:1]
	v_readfirstlane_b32 s45, v9
	v_lshl_add_u64 v[0:1], v[0:1], 0, v[2:3]
	s_mov_b32 m0, s45
	v_add_u32_e32 v9, 32, v7
	global_load_lds_dwordx4 v[0:1], off
	v_add_u32_e32 v0, s3, v9
	v_ashrrev_i32_e32 v1, 31, v0
	v_lshlrev_b64 v[0:1], 11, v[0:1]
	v_add_u32_e32 v10, 0x1000, v82
	v_lshl_add_u64 v[0:1], s[30:31], 0, v[0:1]
	v_readfirstlane_b32 s45, v10
	v_lshl_add_u64 v[0:1], v[0:1], 0, v[2:3]
	s_mov_b32 m0, s45
	v_add_u32_e32 v10, 0x5000, v82
	global_load_lds_dwordx4 v[0:1], off
	v_add_u32_e32 v0, s2, v9
	v_ashrrev_i32_e32 v1, 31, v0
	v_lshlrev_b64 v[0:1], 11, v[0:1]
	v_lshl_add_u64 v[0:1], s[24:25], 0, v[0:1]
	v_readfirstlane_b32 s45, v10
	v_lshl_add_u64 v[0:1], v[0:1], 0, v[2:3]
	s_mov_b32 m0, s45
	v_add_u32_e32 v10, 64, v7
	global_load_lds_dwordx4 v[0:1], off
	v_add_u32_e32 v0, s3, v10
	v_ashrrev_i32_e32 v1, 31, v0
	v_lshlrev_b64 v[0:1], 11, v[0:1]
	v_add_u32_e32 v11, 0x2000, v82
	v_lshl_add_u64 v[0:1], s[30:31], 0, v[0:1]
	v_readfirstlane_b32 s45, v11
	v_lshl_add_u64 v[0:1], v[0:1], 0, v[2:3]
	s_mov_b32 m0, s45
	v_add_u32_e32 v11, 0x6000, v82
	global_load_lds_dwordx4 v[0:1], off
	v_add_u32_e32 v0, s2, v10
	v_ashrrev_i32_e32 v1, 31, v0
	v_lshlrev_b64 v[0:1], 11, v[0:1]
	v_lshl_add_u64 v[0:1], s[24:25], 0, v[0:1]
	v_readfirstlane_b32 s45, v11
	v_lshl_add_u64 v[0:1], v[0:1], 0, v[2:3]
	s_mov_b32 m0, s45
	v_add_u32_e32 v11, 0x60, v7
	global_load_lds_dwordx4 v[0:1], off
	v_add_u32_e32 v0, s3, v11
	v_ashrrev_i32_e32 v1, 31, v0
	v_lshlrev_b64 v[0:1], 11, v[0:1]
	v_add_u32_e32 v12, 0x3000, v82
	v_lshl_add_u64 v[0:1], s[30:31], 0, v[0:1]
	v_readfirstlane_b32 s30, v12
	v_lshl_add_u64 v[0:1], v[0:1], 0, v[2:3]
	s_mov_b32 m0, s30
	s_mov_b32 s4, 0x1ffffc0
	global_load_lds_dwordx4 v[0:1], off
	v_add_u32_e32 v0, s2, v11
	v_ashrrev_i32_e32 v1, 31, v0
	v_lshlrev_b64 v[0:1], 11, v[0:1]
	v_lshl_add_u64 v[0:1], s[24:25], 0, v[0:1]
	v_lshl_add_u64 v[0:1], v[0:1], 0, v[2:3]
	v_add_u32_e32 v2, 0x7000, v82
	v_lshrrev_b32_e32 v5, 4, v4
	v_readfirstlane_b32 s30, v2
	s_mov_b32 m0, s30
	v_bfe_u32 v6, v4, 4, 2
	global_load_lds_dwordx4 v[0:1], off
	v_and_b32_e32 v0, 15, v4
	v_lshrrev_b32_e32 v1, 1, v4
	v_and_or_b32 v0, v1, s4, v0
	v_bfe_u32 v1, v4, 1, 3
	v_lshlrev_b32_e32 v2, 7, v4
	v_bitop3_b32 v5, v5, v1, 3 bitop3:0x6c
	v_bitop3_b32 v4, v8, 7, v4 bitop3:0x48
	v_and_b32_e32 v2, 0x2780, v2
	v_lshlrev_b32_e32 v5, 4, v5
	v_lshlrev_b32_e32 v0, 7, v0
	v_bitop3_b32 v1, v6, v1, 4 bitop3:0x36
	v_lshlrev_b32_e32 v6, 4, v4
	v_add_u32_e32 v4, s37, v7
	v_or_b32_e32 v85, v0, v5
	v_or_b32_e32 v84, v5, v2
	v_ashrrev_i32_e32 v5, 31, v4
	v_lshlrev_b64 v[4:5], 11, v[4:5]
	v_or_b32_e32 v4, v4, v6
	s_waitcnt vmcnt(0)
	v_lshl_add_u64 v[68:69], s[28:29], 0, v[4:5]
	v_add_u32_e32 v4, s43, v9
	v_readlane_b32 s4, v254, 49
	v_ashrrev_i32_e32 v5, 31, v4
	s_add_u32 s30, s4, s44
	v_readlane_b32 s4, v254, 50
	v_lshlrev_b64 v[4:5], 11, v[4:5]
	s_addc_u32 s31, s4, 0
	v_or_b32_e32 v4, v4, v6
	v_lshl_add_u64 v[70:71], s[30:31], 0, v[4:5]
	v_add_u32_e32 v4, s37, v9
	v_ashrrev_i32_e32 v5, 31, v4
	v_lshlrev_b64 v[4:5], 11, v[4:5]
	v_or_b32_e32 v4, v4, v6
	v_lshl_add_u64 v[72:73], s[28:29], 0, v[4:5]
	v_add_u32_e32 v4, s43, v10
	v_ashrrev_i32_e32 v5, 31, v4
	v_lshlrev_b64 v[4:5], 11, v[4:5]
	v_or_b32_e32 v4, v4, v6
	v_lshl_add_u64 v[74:75], s[30:31], 0, v[4:5]
	v_add_u32_e32 v4, s37, v10
	v_ashrrev_i32_e32 v5, 31, v4
	v_lshlrev_b64 v[4:5], 11, v[4:5]
	v_or_b32_e32 v4, v4, v6
	v_lshl_add_u64 v[76:77], s[28:29], 0, v[4:5]
	v_add_u32_e32 v4, s43, v11
	v_ashrrev_i32_e32 v5, 31, v4
	v_lshlrev_b64 v[4:5], 11, v[4:5]
	v_or_b32_e32 v4, v4, v6
	v_lshlrev_b32_e32 v1, 4, v1
	v_lshl_add_u64 v[78:79], s[30:31], 0, v[4:5]
	v_add_u32_e32 v4, s37, v11
	v_or_b32_e32 v83, v1, v0
	v_add_u32_e32 v0, s43, v7
	v_ashrrev_i32_e32 v5, 31, v4
	v_or_b32_e32 v2, v1, v2
	v_ashrrev_i32_e32 v1, 31, v0
	v_lshlrev_b64 v[4:5], 11, v[4:5]
	s_waitcnt vmcnt(0)
	v_lshlrev_b64 v[0:1], 11, v[0:1]
	v_or_b32_e32 v4, v4, v6
	v_or_b32_e32 v0, v0, v6
	v_lshl_add_u64 v[80:81], s[28:29], 0, v[4:5]
	v_mov_b32_e32 v4, 0
	s_mov_b32 s34, 0
	v_lshl_add_u64 v[0:1], s[30:31], 0, v[0:1]
	s_mov_b64 s[30:31], 0
	v_mov_b32_e32 v5, v4
	v_mov_b32_e32 v6, v4
	v_mov_b32_e32 v7, v4
	v_mov_b32_e32 v8, v4
	v_mov_b32_e32 v9, v4
	v_mov_b32_e32 v10, v4
	v_mov_b32_e32 v11, v4
	v_mov_b32_e32 v12, v4
	v_mov_b32_e32 v13, v4
	v_mov_b32_e32 v14, v4
	v_mov_b32_e32 v15, v4
	v_mov_b32_e32 v16, v4
	v_mov_b32_e32 v17, v4
	v_mov_b32_e32 v18, v4
	v_mov_b32_e32 v19, v4
	v_mov_b32_e32 v20, v4
	v_mov_b32_e32 v21, v4
	v_mov_b32_e32 v22, v4
	v_mov_b32_e32 v23, v4
	v_mov_b32_e32 v24, v4
	v_mov_b32_e32 v25, v4
	v_mov_b32_e32 v26, v4
	v_mov_b32_e32 v27, v4
	v_mov_b32_e32 v28, v4
	v_mov_b32_e32 v29, v4
	v_mov_b32_e32 v30, v4
	v_mov_b32_e32 v31, v4
	v_mov_b32_e32 v32, v4
	v_mov_b32_e32 v33, v4
	v_mov_b32_e32 v34, v4
	v_mov_b32_e32 v35, v4
	v_mov_b32_e32 v36, v4
	v_mov_b32_e32 v37, v4
	v_mov_b32_e32 v38, v4
	v_mov_b32_e32 v39, v4
	v_mov_b32_e32 v40, v4
	v_mov_b32_e32 v41, v4
	v_mov_b32_e32 v42, v4
	v_mov_b32_e32 v43, v4
	v_mov_b32_e32 v44, v4
	v_mov_b32_e32 v45, v4
	v_mov_b32_e32 v46, v4
	v_mov_b32_e32 v47, v4
	v_mov_b32_e32 v48, v4
	v_mov_b32_e32 v49, v4
	v_mov_b32_e32 v50, v4
	v_mov_b32_e32 v51, v4
	v_mov_b32_e32 v52, v4
	v_mov_b32_e32 v53, v4
	v_mov_b32_e32 v54, v4
	v_mov_b32_e32 v55, v4
	v_mov_b32_e32 v56, v4
	v_mov_b32_e32 v57, v4
	v_mov_b32_e32 v58, v4
	v_mov_b32_e32 v59, v4
	v_mov_b32_e32 v60, v4
	v_mov_b32_e32 v61, v4
	v_mov_b32_e32 v62, v4
	v_mov_b32_e32 v63, v4
	v_mov_b32_e32 v64, v4
	v_mov_b32_e32 v65, v4
	v_mov_b32_e32 v66, v4
	v_mov_b32_e32 v67, v4
	v_subrev_u32_e32 v150, s46, v0
	v_subrev_u32_e32 v151, s46, v68
	v_subrev_u32_e32 v152, s46, v70
	v_subrev_u32_e32 v153, s46, v72
	v_subrev_u32_e32 v154, s46, v74
	v_subrev_u32_e32 v155, s46, v76
	v_subrev_u32_e32 v156, s46, v78
	v_subrev_u32_e32 v157, s46, v80
	v_readfirstlane_b32 vcc_hi, v82
	s_and_b32 s37, s34, 0x8000
	s_xor_b32 s43, s37, 0x8000
	s_add_i32 s43, s43, vcc_hi
; __device__ __forceinline__ void gemm_mainloop_d(const bf16_t* __restrict__ Ap, int lda, const bf16_t* __restrict__ Bt, int K,
;                                                 int m0, int n0, f32x4 (&acc)[4][4], char* lds) {
;     ...
;   for (int kt = 0; kt < nk; kt++) {
;     const int st = kt & 1;
;     if (kt + 1 < nk) dma(kt + 1, st ^ 1);
;     const char* la = lds + st * 32768; const char* lb = la + 16384;
;     bf16x8 af[2][4], bfv[2][4];
; #pragma unroll
;     for (int kc = 0; kc < 2; kc++) {
; #pragma unroll
;       for (int m = 0; m < 4; m++) { const int row = wr * 64 + m * 16 + fr; af[kc][m] = *(const bf16x8*)(la + (row * 8 + ((kc * 4 + fq) ^ ((row >> 1) & 7))) * 16); }
; #pragma unroll
;       for (int n = 0; n < 4; n++) { const int row = wc * 64 + n * 16 + fr; bfv[kc][n] = *(const bf16x8*)(lb + (row * 8 + ((kc * 4 + fq) ^ ((row >> 1) & 7))) * 16); }
;     }
;     __builtin_amdgcn_s_setprio(1);
; #pragma unroll
;     for (int kc = 0; kc < 2; kc++)
; #pragma unroll
;       for (int m = 0; m < 4; m++)
; #pragma unroll
;         for (int n = 0; n < 4; n++) acc[m][n] = __builtin_amdgcn_mfma_f32_16x16x32_bf16(bfv[kc][n], af[kc][m], acc[m][n], 0, 0, 0);
;     __builtin_amdgcn_s_setprio(0);
;     asm volatile("s_waitcnt vmcnt(0) lgkmcnt(0)" ::: "memory"); __builtin_amdgcn_s_barrier(); asm volatile("" ::: "memory");
;   }
.LBB0_126:
	s_barrier
	s_setprio 3
	s_mov_b32 m0, s43
	s_add_i32 vcc_lo, s43, 0x4000
	global_load_lds_dwordx4 v150, s[46:47]
	s_mov_b32 m0, vcc_lo
	s_add_i32 vcc_lo, s43, 0x1000
	global_load_lds_dwordx4 v151, s[46:47]
	s_mov_b32 m0, vcc_lo
	s_add_i32 vcc_lo, s43, 0x5000
	global_load_lds_dwordx4 v152, s[46:47]
	s_mov_b32 m0, vcc_lo
	s_add_i32 vcc_lo, s43, 0x2000
	global_load_lds_dwordx4 v153, s[46:47]
	s_mov_b32 m0, vcc_lo
	s_add_i32 vcc_lo, s43, 0x6000
	global_load_lds_dwordx4 v154, s[46:47]
	s_mov_b32 m0, vcc_lo
	s_add_i32 vcc_lo, s43, 0x3000
	global_load_lds_dwordx4 v155, s[46:47]
	s_mov_b32 m0, vcc_lo
	s_add_i32 vcc_lo, s43, 0x7000
	global_load_lds_dwordx4 v156, s[46:47]
	s_mov_b32 m0, vcc_lo
	s_nop 0
	global_load_lds_dwordx4 v157, s[46:47]
	v_add_u32_e32 v150, 0x80, v150
	v_add_u32_e32 v151, 0x80, v151
	v_add_u32_e32 v152, 0x80, v152
	v_add_u32_e32 v153, 0x80, v153
	v_add_u32_e32 v154, 0x80, v154
	v_add_u32_e32 v155, 0x80, v155
	v_add_u32_e32 v156, 0x80, v156
	v_add_u32_e32 v157, 0x80, v157
	v_add_u32_e32 v98, s37, v85
	v_add_u32_e32 v114, s37, v84
	v_add_u32_e32 v130, s37, v83
	v_add_u32_e32 v146, s37, v2
	ds_read_b128 v[86:89], v98
	ds_read_b128 v[90:93], v98 offset:2048
	ds_read_b128 v[94:97], v98 offset:4096
	ds_read_b128 v[98:101], v98 offset:6144
	ds_read_b128 v[102:105], v114 offset:16384
	ds_read_b128 v[106:109], v114 offset:18432
	ds_read_b128 v[110:113], v114 offset:20480
	ds_read_b128 v[114:117], v114 offset:22528
	ds_read_b128 v[118:121], v130
	ds_read_b128 v[122:125], v130 offset:2048
	ds_read_b128 v[126:129], v130 offset:4096
	ds_read_b128 v[130:133], v130 offset:6144
	ds_read_b128 v[134:137], v146 offset:16384
	ds_read_b128 v[138:141], v146 offset:18432
	ds_read_b128 v[142:145], v146 offset:20480
	ds_read_b128 v[146:149], v146 offset:22528
	s_setprio 1
	s_waitcnt lgkmcnt(0)
	v_mfma_f32_16x16x32_bf16 v[64:67], v[102:105], v[86:89], v[64:67]
	v_mfma_f32_16x16x32_bf16 v[60:63], v[106:109], v[86:89], v[60:63]
	v_mfma_f32_16x16x32_bf16 v[56:59], v[110:113], v[86:89], v[56:59]
	v_mfma_f32_16x16x32_bf16 v[52:55], v[114:117], v[86:89], v[52:55]
	v_mfma_f32_16x16x32_bf16 v[48:51], v[102:105], v[90:93], v[48:51]
	v_mfma_f32_16x16x32_bf16 v[44:47], v[106:109], v[90:93], v[44:47]
	v_mfma_f32_16x16x32_bf16 v[40:43], v[110:113], v[90:93], v[40:43]
	v_mfma_f32_16x16x32_bf16 v[36:39], v[114:117], v[90:93], v[36:39]
	v_mfma_f32_16x16x32_bf16 v[32:35], v[102:105], v[94:97], v[32:35]
	v_mfma_f32_16x16x32_bf16 v[28:31], v[106:109], v[94:97], v[28:31]
	v_mfma_f32_16x16x32_bf16 v[24:27], v[110:113], v[94:97], v[24:27]
	v_mfma_f32_16x16x32_bf16 v[20:23], v[114:117], v[94:97], v[20:23]
	v_mfma_f32_16x16x32_bf16 v[16:19], v[102:105], v[98:101], v[16:19]
	v_mfma_f32_16x16x32_bf16 v[12:15], v[106:109], v[98:101], v[12:15]
	v_mfma_f32_16x16x32_bf16 v[8:11], v[110:113], v[98:101], v[8:11]
	v_mfma_f32_16x16x32_bf16 v[4:7], v[114:117], v[98:101], v[4:7]
	v_mfma_f32_16x16x32_bf16 v[64:67], v[134:137], v[118:121], v[64:67]
	v_mfma_f32_16x16x32_bf16 v[60:63], v[138:141], v[118:121], v[60:63]
	v_mfma_f32_16x16x32_bf16 v[56:59], v[142:145], v[118:121], v[56:59]
	v_mfma_f32_16x16x32_bf16 v[52:55], v[146:149], v[118:121], v[52:55]
	v_mfma_f32_16x16x32_bf16 v[48:51], v[134:137], v[122:125], v[48:51]
	v_mfma_f32_16x16x32_bf16 v[44:47], v[138:141], v[122:125], v[44:47]
	v_mfma_f32_16x16x32_bf16 v[40:43], v[142:145], v[122:125], v[40:43]
	v_mfma_f32_16x16x32_bf16 v[36:39], v[146:149], v[122:125], v[36:39]
	v_mfma_f32_16x16x32_bf16 v[32:35], v[134:137], v[126:129], v[32:35]
	v_mfma_f32_16x16x32_bf16 v[28:31], v[138:141], v[126:129], v[28:31]
	v_mfma_f32_16x16x32_bf16 v[24:27], v[142:145], v[126:129], v[24:27]
	v_mfma_f32_16x16x32_bf16 v[20:23], v[146:149], v[126:129], v[20:23]
	v_mfma_f32_16x16x32_bf16 v[16:19], v[134:137], v[130:133], v[16:19]
	v_mfma_f32_16x16x32_bf16 v[12:15], v[138:141], v[130:133], v[12:15]
	v_mfma_f32_16x16x32_bf16 v[8:11], v[142:145], v[130:133], v[8:11]
	v_mfma_f32_16x16x32_bf16 v[4:7], v[146:149], v[130:133], v[4:7]
	s_setprio 0
	s_waitcnt vmcnt(0) lgkmcnt(0)
	s_add_u32 s30, s30, 0x80
	s_addc_u32 s31, s31, 0
	s_add_i32 s34, s34, 0x8000
	s_and_b32 s37, s34, 0x8000
	s_xor_b32 s43, s37, 0x8000
	s_add_i32 s43, s43, vcc_hi
	s_cmpk_eq_i32 s30, 0x780
	s_cbranch_scc0 .LBB0_126
	s_barrier
; __device__ __forceinline__ void gemm_mainloop_d(const bf16_t* __restrict__ Ap, int lda, const bf16_t* __restrict__ Bt, int K,
;                                                 int m0, int n0, f32x4 (&acc)[4][4], char* lds) {
;     ...
;     const char* la = lds + st * 32768; const char* lb = la + 16384;
;     bf16x8 af[2][4], bfv[2][4];
; #pragma unroll
;     for (int kc = 0; kc < 2; kc++) {
; #pragma unroll
;       for (int m = 0; m < 4; m++) { const int row = wr * 64 + m * 16 + fr; af[kc][m] = *(const bf16x8*)(la + (row * 8 + ((kc * 4 + fq) ^ ((row >> 1) & 7))) * 16); }
; #pragma unroll
;       for (int n = 0; n < 4; n++) { const int row = wc * 64 + n * 16 + fr; bfv[kc][n] = *(const bf16x8*)(lb + (row * 8 + ((kc * 4 + fq) ^ ((row >> 1) & 7))) * 16); }
;     }
;     __builtin_amdgcn_s_setprio(1);
; #pragma unroll
;     for (int kc = 0; kc < 2; kc++)
; #pragma unroll
;       for (int m = 0; m < 4; m++)
; #pragma unroll
;         for (int n = 0; n < 4; n++) acc[m][n] = __builtin_amdgcn_mfma_f32_16x16x32_bf16(bfv[kc][n], af[kc][m], acc[m][n], 0, 0, 0);
;     __builtin_amdgcn_s_setprio(0);
;     asm volatile("s_waitcnt vmcnt(0) lgkmcnt(0)" ::: "memory"); __builtin_amdgcn_s_barrier(); asm volatile("" ::: "memory");
	v_add_u32_e32 v0, 0, v85
	ds_read_b128 v[68:71], v0 offset:32768
	ds_read_b128 v[72:75], v0 offset:34816
	ds_read_b128 v[76:79], v0 offset:36864
	ds_read_b128 v[86:89], v0 offset:38912
	v_add_u32_e32 v0, 0, v84
	ds_read_b128 v[90:93], v0 offset:49152
	ds_read_b128 v[94:97], v0 offset:51200
	ds_read_b128 v[98:101], v0 offset:53248
	ds_read_b128 v[102:105], v0 offset:55296
	v_add_u32_e32 v0, 0, v83
	s_add_u32 s30, s46, s35
	ds_read_b128 v[80:83], v0 offset:32768
	ds_read_b128 v[106:109], v0 offset:34816
	ds_read_b128 v[110:113], v0 offset:36864
	ds_read_b128 v[114:117], v0 offset:38912
	v_add_u32_e32 v0, 0, v2
	s_addc_u32 s31, s47, 0
	ds_read_b128 v[118:121], v0 offset:49152
	ds_read_b128 v[122:125], v0 offset:51200
	ds_read_b128 v[126:129], v0 offset:53248
	ds_read_b128 v[130:133], v0 offset:55296
	s_add_u32 s36, s46, s36
	s_addc_u32 s37, s47, 0
	s_add_u32 s34, s30, 0x65a8000
	s_addc_u32 s35, s31, 0
	s_add_u32 s30, s36, 0xff9c000
	s_addc_u32 s31, s37, 0
	s_setprio 1
	s_waitcnt lgkmcnt(0)
	v_mfma_f32_16x16x32_bf16 v[56:59], v[98:101], v[68:71], v[56:59]
	v_mfma_f32_16x16x32_bf16 v[48:51], v[90:93], v[72:75], v[48:51]
	v_mfma_f32_16x16x32_bf16 v[44:47], v[94:97], v[72:75], v[44:47]
	v_mfma_f32_16x16x32_bf16 v[40:43], v[98:101], v[72:75], v[40:43]
	v_mfma_f32_16x16x32_bf16 v[36:39], v[102:105], v[72:75], v[36:39]
	v_mfma_f32_16x16x32_bf16 v[32:35], v[90:93], v[76:79], v[32:35]
	v_mfma_f32_16x16x32_bf16 v[28:31], v[94:97], v[76:79], v[28:31]
	v_mfma_f32_16x16x32_bf16 v[24:27], v[98:101], v[76:79], v[24:27]
	v_mfma_f32_16x16x32_bf16 v[20:23], v[102:105], v[76:79], v[20:23]
	v_mfma_f32_16x16x32_bf16 v[16:19], v[90:93], v[86:89], v[16:19]
	v_mfma_f32_16x16x32_bf16 v[12:15], v[94:97], v[86:89], v[12:15]
	v_mfma_f32_16x16x32_bf16 v[8:11], v[98:101], v[86:89], v[8:11]
	v_mfma_f32_16x16x32_bf16 v[4:7], v[102:105], v[86:89], v[4:7]
	v_mfma_f32_16x16x32_bf16 v[64:67], v[90:93], v[68:71], v[64:67]
	v_mfma_f32_16x16x32_bf16 v[60:63], v[94:97], v[68:71], v[60:63]
	v_mfma_f32_16x16x32_bf16 v[52:55], v[102:105], v[68:71], v[52:55]
	v_mfma_f32_16x16x32_bf16 v[56:59], v[126:129], v[80:83], v[56:59]
	v_mfma_f32_16x16x32_bf16 v[48:51], v[118:121], v[106:109], v[48:51]
	v_mfma_f32_16x16x32_bf16 v[44:47], v[122:125], v[106:109], v[44:47]
	v_mfma_f32_16x16x32_bf16 v[40:43], v[126:129], v[106:109], v[40:43]
	v_mfma_f32_16x16x32_bf16 v[36:39], v[130:133], v[106:109], v[36:39]
	v_mfma_f32_16x16x32_bf16 v[32:35], v[118:121], v[110:113], v[32:35]
	v_mfma_f32_16x16x32_bf16 v[28:31], v[122:125], v[110:113], v[28:31]
	v_mfma_f32_16x16x32_bf16 v[24:27], v[126:129], v[110:113], v[24:27]
	v_mfma_f32_16x16x32_bf16 v[20:23], v[130:133], v[110:113], v[20:23]
	v_mfma_f32_16x16x32_bf16 v[16:19], v[118:121], v[114:117], v[16:19]
	v_mfma_f32_16x16x32_bf16 v[12:15], v[122:125], v[114:117], v[12:15]
	v_mfma_f32_16x16x32_bf16 v[8:11], v[126:129], v[114:117], v[8:11]
	v_mfma_f32_16x16x32_bf16 v[4:7], v[130:133], v[114:117], v[4:7]
	v_mfma_f32_16x16x32_bf16 v[64:67], v[118:121], v[80:83], v[64:67]
	v_mfma_f32_16x16x32_bf16 v[60:63], v[122:125], v[80:83], v[60:63]
	v_mfma_f32_16x16x32_bf16 v[68:71], v[130:133], v[80:83], v[52:55]
	s_setprio 0
	v_mov_b32_e32 v0, v198
	s_waitcnt vmcnt(0) lgkmcnt(0)
	s_barrier
; __device__ __forceinline__ unsigned pk2(float lo, float hi) { unsigned r; asm("v_cvt_pk_bf16_f32 %0, %1, %2" : "=v"(r) : "v"(lo), "v"(hi)); return r; }
; __device__ __forceinline__ float bflo(unsigned u) { return __uint_as_float(u << 16); }
; __device__ __forceinline__ float bfhi(unsigned u) { return __uint_as_float(u & 0xffff0000u); }
; __device__ __forceinline__ void gemm_RES(const bf16_t* A, int K, const bf16_t* Bt, const float* xin, float* xout, bf16_t* xb, float* rss, int item, char* lds) {
;     ...
; #pragma unroll
;   for (int m = 0; m < 4; m++) {
;     const int rowg = m0 + wr * 64 + m * 16 + fr;
;     const size_t ro = (size_t)rowg * DM;
;     float sq = 0.f;
; #pragma unroll
;     for (int n = 0; n < 4; n++) {
;       const int col = n0 + wc * 64 + n * 16 + fq * 4;
;       f32x4 xv = *(const f32x4*)(xin + ro + col);
;       const f32x4 xn = xv + acc[m][n];
;       *(f32x4*)(xout + ro + col) = xn;
;       u32x2 w; w[0] = pk2(xn[0], xn[1]); w[1] = pk2(xn[2], xn[3]); *(u32x2*)(xb + ro + col) = w;
;       const float b0 = bflo(w[0]), b1 = bfhi(w[0]), b2 = bflo(w[1]), b3 = bfhi(w[1]);
;       sq += b0 * b0 + b1 * b1 + b2 * b2 + b3 * b3;
;     }
;     sq += __shfl_xor(sq, 16); sq += __shfl_xor(sq, 32);
;     if (fq == 0) unsafeAtomicAdd(rss + rowg, sq);
;   }
	v_readlane_b32 s4, v252, 35
	v_ashrrev_i32_e32 v2, 1, v0
	v_and_b32_e32 v2, 0xffffffc0, v2
	v_add_u32_e32 v2, s3, v2
	v_bfe_u32 v82, v0, 4, 2
	v_and_or_b32 v52, v0, 15, v2
	v_and_b32_e32 v1, 64, v0
	v_lshlrev_b32_e32 v0, 2, v82
	v_ashrrev_i32_e32 v53, 31, v52
	v_or3_b32 v78, v0, v1, s2
	v_lshlrev_b64 v[54:55], 12, v[52:53]
	v_lshl_add_u64 v[0:1], s[26:27], 0, v[54:55]
	v_lshlrev_b32_e32 v2, 2, v78
	v_lshl_add_u64 v[76:77], v[0:1], 0, v[2:3]
	global_load_dwordx4 v[72:75], v[76:77], off
	v_lshlrev_b32_e32 v0, 1, v78
	v_lshlrev_b64 v[78:79], 11, v[52:53]
	v_readlane_b32 s18, v252, 49
	v_readlane_b32 s19, v252, 50
	v_mov_b32_e32 v1, v3
	v_lshl_add_u64 v[78:79], s[34:35], 0, v[78:79]
	v_lshl_add_u64 v[54:55], s[18:19], 0, v[54:55]
	v_lshl_add_u64 v[80:81], v[54:55], 0, v[2:3]
	v_lshl_add_u64 v[78:79], v[78:79], 0, v[0:1]
	v_readlane_b32 s5, v252, 36
	v_readlane_b32 s6, v252, 37
	v_readlane_b32 s7, v252, 38
	v_readlane_b32 s8, v252, 39
	v_readlane_b32 s9, v252, 40
	v_readlane_b32 s10, v252, 41
	v_readlane_b32 s11, v252, 42
	v_readlane_b32 s12, v252, 43
	v_readlane_b32 s13, v252, 44
	v_readlane_b32 s14, v252, 45
	v_readlane_b32 s15, v252, 46
	v_readlane_b32 s16, v252, 47
	v_readlane_b32 s17, v252, 48
	s_waitcnt vmcnt(0)
	v_pk_add_f32 v[66:67], v[66:67], v[74:75]
	v_pk_add_f32 v[64:65], v[64:65], v[72:73]
	global_store_dwordx4 v[80:81], v[64:67], off
	v_cvt_pk_bf16_f32 v54, v64, v65
	v_cvt_pk_bf16_f32 v55, v66, v67
	global_store_dwordx2 v[78:79], v[54:55], off
	global_load_dwordx4 v[64:67], v[76:77], off offset:64
	s_waitcnt vmcnt(0)
	v_pk_add_f32 v[62:63], v[62:63], v[66:67]
	v_pk_add_f32 v[60:61], v[60:61], v[64:65]
	global_store_dwordx4 v[80:81], v[60:63], off offset:64
	v_cvt_pk_bf16_f32 v64, v60, v61
	v_cvt_pk_bf16_f32 v65, v62, v63
	global_store_dwordx2 v[78:79], v[64:65], off offset:32
	global_load_dwordx4 v[60:63], v[76:77], off offset:128
	v_lshlrev_b32_e32 v66, 16, v54
	v_and_b32_e32 v54, 0xffff0000, v54
	v_mul_f32_e32 v54, v54, v54
	v_lshlrev_b32_e32 v67, 16, v55
	v_fmac_f32_e32 v54, v66, v66
	v_and_b32_e32 v55, 0xffff0000, v55
	v_fmac_f32_e32 v54, v67, v67
	v_fmac_f32_e32 v54, v55, v55
	v_lshlrev_b32_e32 v55, 16, v64
	v_and_b32_e32 v64, 0xffff0000, v64
	v_mul_f32_e32 v64, v64, v64
	v_lshlrev_b32_e32 v66, 16, v65
	v_fmac_f32_e32 v64, v55, v55
	v_and_b32_e32 v65, 0xffff0000, v65
	v_fmac_f32_e32 v64, v66, v66
	v_fmac_f32_e32 v64, v65, v65
	v_add_f32_e32 v54, v54, v64
	s_waitcnt vmcnt(0)
	v_pk_add_f32 v[58:59], v[58:59], v[62:63]
	v_pk_add_f32 v[56:57], v[56:57], v[60:61]
	global_store_dwordx4 v[80:81], v[56:59], off offset:128
	v_cvt_pk_bf16_f32 v62, v56, v57
	v_cvt_pk_bf16_f32 v63, v58, v59
	global_store_dwordx2 v[78:79], v[62:63], off offset:64
	global_load_dwordx4 v[58:61], v[76:77], off offset:192
	v_lshlrev_b32_e32 v55, 16, v62
	v_and_b32_e32 v62, 0xffff0000, v62
	v_mul_f32_e32 v62, v62, v62
	v_lshlrev_b32_e32 v64, 16, v63
	v_fmac_f32_e32 v62, v55, v55
	v_and_b32_e32 v63, 0xffff0000, v63
	v_fmac_f32_e32 v62, v64, v64
	v_fmac_f32_e32 v62, v63, v63
	v_add_f32_e32 v54, v54, v62
	v_and_b32_e32 v57, 64, v218
	v_xor_b32_e32 v56, 16, v218
	v_add_u32_e32 v57, 64, v57
	v_cmp_lt_i32_e32 vcc, v56, v57
	s_waitcnt vmcnt(0)
	v_pk_add_f32 v[58:59], v[68:69], v[58:59]
	s_nop 0
	v_cvt_pk_bf16_f32 v62, v58, v59
	v_pk_add_f32 v[60:61], v[70:71], v[60:61]
	v_and_b32_e32 v64, 0xffff0000, v62
	v_lshlrev_b32_e32 v55, 16, v62
	v_mul_f32_e32 v64, v64, v64
	v_cvt_pk_bf16_f32 v63, v60, v61
	v_fmac_f32_e32 v64, v55, v55
	v_lshlrev_b32_e32 v65, 16, v63
	v_and_b32_e32 v66, 0xffff0000, v63
	v_fmac_f32_e32 v64, v65, v65
	v_cndmask_b32_e32 v56, v218, v56, vcc
	v_fmac_f32_e32 v64, v66, v66
	v_lshlrev_b32_e32 v56, 2, v56
	v_add_f32_e32 v54, v54, v64
	ds_bpermute_b32 v55, v56, v54
	v_xor_b32_e32 v64, 32, v218
	v_cmp_lt_i32_e32 vcc, v64, v57
	global_store_dwordx4 v[80:81], v[58:61], off offset:192
	global_store_dwordx2 v[78:79], v[62:63], off offset:96
	v_cndmask_b32_e32 v57, v218, v64, vcc
	s_waitcnt lgkmcnt(0)
	v_add_f32_e32 v54, v54, v55
	v_lshlrev_b32_e32 v57, 2, v57
	ds_bpermute_b32 v55, v57, v54
	v_cmp_eq_u32_e32 vcc, 0, v82
	s_and_saveexec_b64 s[36:37], vcc
	s_cbranch_execz .LBB0_129
	v_lshl_add_u64 v[58:59], v[52:53], 2, s[30:31]
	s_waitcnt lgkmcnt(0)
	v_add_f32_e32 v53, v54, v55
	global_atomic_add_f32 v[58:59], v53, off

; __device__ __forceinline__ unsigned char* WS(const Params& p) { unsigned z = 0; asm volatile("" : "+s"(z)); return p.ws + z; }
; __device__ __forceinline__ int opaque_tid() { int t = threadIdx.x; asm volatile("" : "+v"(t)); return t; }
; __device__ __forceinline__ void gemm_mainloop_d(const bf16_t* __restrict__ Ap, int lda, const bf16_t* __restrict__ Bt, int K,
;                                                 int m0, int n0, f32x4 (&acc)[4][4], char* lds) {
;   const int tid = opaque_tid(), lane = tid & 63, wid = tid >> 6, wr = wid >> 1, wc = wid & 1, fr = lane & 15, fq = lane >> 4;
; #pragma unroll
;   for (int m = 0; m < 4; m++)
; #pragma unroll
;     for (int n = 0; n < 4; n++) acc[m][n] = (f32x4){0.f, 0.f, 0.f, 0.f};
;   const int nk = K >> 6;
;   const int lrow = tid >> 3, cph = tid & 7;
;   auto dma = [&](int kt, int st) {
;     char* la = lds + st * 32768; char* lb = la + 16384;
; #pragma unroll
;     for (int i = 0; i < 4; i++) {
;       const int row = i * 32 + lrow; const int c = cph ^ ((row >> 1) & 7);
;       __builtin_amdgcn_global_load_lds((const unsigned*)(Ap + (size_t)(m0 + row) * lda + kt * 64 + c * 8), (__attribute__((address_space(3))) unsigned*)(la + i * 4096 + tid * 16), 16, 0, 0);
;       __builtin_amdgcn_global_load_lds((const unsigned*)(Bt + (size_t)(n0 + row) * K + kt * 64 + c * 8), (__attribute__((address_space(3))) unsigned*)(lb + i * 4096 + tid * 16), 16, 0, 0);
;     }
;   };
;   dma(0, 0);
;   asm volatile("s_waitcnt vmcnt(0)" ::: "memory"); __builtin_amdgcn_s_barrier(); asm volatile("" ::: "memory");
; __device__ __forceinline__ void gemm_A(const Params& p, int item, char* lds) {
;   const int mt = item / 18, nt = item % 18; const int m0 = mt * 128, n0 = nt * 128;
;   f32x4 acc[4][4];
;   gemm_mainloop_d((const bf16_t*)(WS(p) + OFF_XB), DM, (const bf16_t*)(WS(p) + OFF_WIN), DM, m0, n0, acc, lds);
.LBB0_656:
	s_lshr_b32 s3, s66, 3
	s_mul_hi_u32 s30, s3, 0xe38e38f
	s_mul_i32 s31, s30, 18
	s_sub_u32 s2, s3, s31
	s_and_b32 s31, s66, 7
	s_lshl_b32 s30, s30, 3
	s_add_u32 s30, s30, s31
	s_lshl_b32 s24, s30, 7
	s_lshl_b32 s3, s2, 7
	s_mov_b32 s30, 0
	s_mov_b32 s31, 0
	v_mov_b32_e32 v20, v198
	s_add_u32 s26, s46, s30
	s_addc_u32 s27, s47, 0
	v_ashrrev_i32_e32 v16, 3, v20
	v_lshrrev_b32_e32 v23, 1, v16
	v_add_u32_e32 v0, s24, v16
	s_add_u32 s28, s26, 0x65a8000
	v_xor_b32_e32 v2, v23, v20
	v_ashrrev_i32_e32 v1, 31, v0
	s_addc_u32 s29, s27, 0
	v_lshlrev_b64 v[0:1], 11, v[0:1]
	v_lshlrev_b32_e32 v2, 4, v2
	v_lshl_add_u32 v82, v20, 4, 0
	s_waitcnt lgkmcnt(0)
	v_lshl_add_u64 v[4:5], s[28:29], 0, v[0:1]
	v_and_b32_e32 v2, 0x70, v2
	v_readfirstlane_b32 s34, v82
	s_add_u32 s26, s46, s31
	v_lshl_add_u64 v[4:5], v[4:5], 0, v[2:3]
	s_mov_b32 m0, s34
	s_addc_u32 s27, s47, 0
	global_load_lds_dwordx4 v[4:5], off
	v_add_u32_e32 v4, s3, v16
	s_add_u32 s26, s26, 0x8000
	v_ashrrev_i32_e32 v5, 31, v4
	s_addc_u32 s27, s27, 0
	v_lshlrev_b64 v[4:5], 11, v[4:5]
	v_add_u32_e32 v8, 0x4000, v82
	v_lshl_add_u64 v[6:7], s[26:27], 0, v[4:5]
	v_readfirstlane_b32 s34, v8
	v_lshl_add_u64 v[6:7], v[6:7], 0, v[2:3]
	s_mov_b32 m0, s34
	v_add_u32_e32 v10, 32, v16
	global_load_lds_dwordx4 v[6:7], off
	v_add_u32_e32 v6, s24, v10
	v_ashrrev_i32_e32 v7, 31, v6
	v_lshlrev_b64 v[6:7], 11, v[6:7]
	v_add_u32_e32 v11, 0x1000, v82
	v_lshl_add_u64 v[8:9], s[28:29], 0, v[6:7]
	v_readfirstlane_b32 s34, v11
	v_lshl_add_u64 v[8:9], v[8:9], 0, v[2:3]
	s_mov_b32 m0, s34
	v_add_u32_e32 v12, 0x5000, v82
	global_load_lds_dwordx4 v[8:9], off
	v_add_u32_e32 v8, s3, v10
	v_ashrrev_i32_e32 v9, 31, v8
	v_lshlrev_b64 v[8:9], 11, v[8:9]
	v_lshl_add_u64 v[10:11], s[26:27], 0, v[8:9]
	v_readfirstlane_b32 s34, v12
	v_lshl_add_u64 v[10:11], v[10:11], 0, v[2:3]
	s_mov_b32 m0, s34
	v_add_u32_e32 v14, 64, v16
	global_load_lds_dwordx4 v[10:11], off
	v_add_u32_e32 v10, s24, v14
	v_ashrrev_i32_e32 v11, 31, v10
	v_lshlrev_b64 v[10:11], 11, v[10:11]
	v_add_u32_e32 v15, 0x2000, v82
	v_lshl_add_u64 v[12:13], s[28:29], 0, v[10:11]
	v_readfirstlane_b32 s34, v15
	v_lshl_add_u64 v[12:13], v[12:13], 0, v[2:3]
	s_mov_b32 m0, s34
	v_add_u32_e32 v17, 0x6000, v82
	global_load_lds_dwordx4 v[12:13], off
	v_add_u32_e32 v12, s3, v14
	v_ashrrev_i32_e32 v13, 31, v12
	v_lshlrev_b64 v[12:13], 11, v[12:13]
	v_lshl_add_u64 v[14:15], s[26:27], 0, v[12:13]
	v_readfirstlane_b32 s34, v17
	v_lshl_add_u64 v[14:15], v[14:15], 0, v[2:3]
	s_mov_b32 m0, s34
	v_add_u32_e32 v18, 0x60, v16
	global_load_lds_dwordx4 v[14:15], off
	v_add_u32_e32 v14, s24, v18
	v_ashrrev_i32_e32 v15, 31, v14
	v_lshlrev_b64 v[14:15], 11, v[14:15]
	v_add_u32_e32 v19, 0x3000, v82
	v_lshl_add_u64 v[16:17], s[28:29], 0, v[14:15]
	v_readfirstlane_b32 s28, v19
	v_lshl_add_u64 v[16:17], v[16:17], 0, v[2:3]
	s_mov_b32 m0, s28
	s_mov_b32 s4, 0x1ffffc0
	global_load_lds_dwordx4 v[16:17], off
	v_add_u32_e32 v16, s3, v18
	v_ashrrev_i32_e32 v17, 31, v16
	v_lshlrev_b64 v[16:17], 11, v[16:17]
	v_lshl_add_u64 v[18:19], s[26:27], 0, v[16:17]
	v_lshl_add_u64 v[18:19], v[18:19], 0, v[2:3]
	v_add_u32_e32 v2, 0x7000, v82
	v_lshrrev_b32_e32 v21, 4, v20
	v_readfirstlane_b32 s26, v2
	s_mov_b32 m0, s26
	v_and_b32_e32 v2, 15, v20
	global_load_lds_dwordx4 v[18:19], off
	v_lshrrev_b32_e32 v18, 1, v20
	v_bfe_u32 v22, v20, 4, 2
	v_and_or_b32 v2, v18, s4, v2
	v_bfe_u32 v18, v20, 1, 3
	v_lshlrev_b32_e32 v19, 7, v20
	v_bitop3_b32 v21, v21, v18, 3 bitop3:0x6c
	v_bitop3_b32 v18, v22, v18, 4 bitop3:0x36
	v_readlane_b32 s4, v254, 44
	v_and_b32_e32 v19, 0x2780, v19
	v_lshlrev_b32_e32 v21, 4, v21
	v_lshlrev_b32_e32 v2, 7, v2
	v_lshlrev_b32_e32 v18, 4, v18
	s_add_u32 s26, s4, s30
	v_readlane_b32 s4, v254, 45
	v_or_b32_e32 v85, v2, v21
	v_or_b32_e32 v83, v18, v2
	v_or_b32_e32 v2, v18, v19
	v_bitop3_b32 v18, v23, 7, v20 bitop3:0x48
	s_addc_u32 s27, s4, 0
	v_readlane_b32 s4, v254, 62
	v_lshlrev_b32_e32 v18, 4, v18
	s_add_u32 s28, s4, s31
	v_readlane_b32 s4, v254, 63
	s_waitcnt vmcnt(0)
	v_or_b32_e32 v4, v4, v18
	s_addc_u32 s29, s4, 0
	v_or_b32_e32 v0, v0, v18
	s_waitcnt vmcnt(0)
	v_lshl_add_u64 v[68:69], s[28:29], 0, v[4:5]
	v_or_b32_e32 v6, v6, v18
	v_or_b32_e32 v8, v8, v18
	v_or_b32_e32 v10, v10, v18
	v_or_b32_e32 v12, v12, v18
	v_or_b32_e32 v14, v14, v18
	v_or_b32_e32 v16, v16, v18
	v_mov_b32_e32 v4, 0
	s_mov_b32 s25, 0
	v_or_b32_e32 v84, v21, v19
	v_lshl_add_u64 v[0:1], s[26:27], 0, v[0:1]
	v_lshl_add_u64 v[70:71], s[26:27], 0, v[6:7]
	v_lshl_add_u64 v[72:73], s[28:29], 0, v[8:9]
	v_lshl_add_u64 v[74:75], s[26:27], 0, v[10:11]
	v_lshl_add_u64 v[76:77], s[28:29], 0, v[12:13]
	v_lshl_add_u64 v[78:79], s[26:27], 0, v[14:15]
	v_lshl_add_u64 v[80:81], s[28:29], 0, v[16:17]
	s_mov_b64 s[26:27], 0
	v_mov_b32_e32 v5, v4
	v_mov_b32_e32 v6, v4
	v_mov_b32_e32 v7, v4
	v_mov_b32_e32 v8, v4
	v_mov_b32_e32 v9, v4
	v_mov_b32_e32 v10, v4
	v_mov_b32_e32 v11, v4
	v_mov_b32_e32 v12, v4
	v_mov_b32_e32 v13, v4
	v_mov_b32_e32 v14, v4
	v_mov_b32_e32 v15, v4
	v_mov_b32_e32 v16, v4
	v_mov_b32_e32 v17, v4
	v_mov_b32_e32 v18, v4
	v_mov_b32_e32 v19, v4
	v_mov_b32_e32 v20, v4
	v_mov_b32_e32 v21, v4
	v_mov_b32_e32 v22, v4
	v_mov_b32_e32 v23, v4
	v_mov_b32_e32 v24, v4
	v_mov_b32_e32 v25, v4
	v_mov_b32_e32 v26, v4
	v_mov_b32_e32 v27, v4
	v_mov_b32_e32 v28, v4
	v_mov_b32_e32 v29, v4
	v_mov_b32_e32 v30, v4
	v_mov_b32_e32 v31, v4
	v_mov_b32_e32 v32, v4
	v_mov_b32_e32 v33, v4
	v_mov_b32_e32 v34, v4
	v_mov_b32_e32 v35, v4
	v_mov_b32_e32 v36, v4
	v_mov_b32_e32 v37, v4
	v_mov_b32_e32 v38, v4
	v_mov_b32_e32 v39, v4
	v_mov_b32_e32 v40, v4
	v_mov_b32_e32 v41, v4
	v_mov_b32_e32 v42, v4
	v_mov_b32_e32 v43, v4
	v_mov_b32_e32 v44, v4
	v_mov_b32_e32 v45, v4
	v_mov_b32_e32 v46, v4
	v_mov_b32_e32 v47, v4
	v_mov_b32_e32 v48, v4
	v_mov_b32_e32 v49, v4
	v_mov_b32_e32 v50, v4
	v_mov_b32_e32 v51, v4
	v_mov_b32_e32 v52, v4
	v_mov_b32_e32 v53, v4
	v_mov_b32_e32 v54, v4
	v_mov_b32_e32 v55, v4
	v_mov_b32_e32 v56, v4
	v_mov_b32_e32 v57, v4
	v_mov_b32_e32 v58, v4
	v_mov_b32_e32 v59, v4
	v_mov_b32_e32 v60, v4
	v_mov_b32_e32 v61, v4
	v_mov_b32_e32 v62, v4
	v_mov_b32_e32 v63, v4
	v_mov_b32_e32 v64, v4
	v_mov_b32_e32 v65, v4
	v_mov_b32_e32 v66, v4
	v_mov_b32_e32 v67, v4
	v_subrev_u32_e32 v150, s46, v0
	v_subrev_u32_e32 v151, s46, v68
	v_subrev_u32_e32 v152, s46, v70
	v_subrev_u32_e32 v153, s46, v72
	v_subrev_u32_e32 v154, s46, v74
	v_subrev_u32_e32 v155, s46, v76
	v_subrev_u32_e32 v156, s46, v78
	v_subrev_u32_e32 v157, s46, v80
	v_readfirstlane_b32 vcc_hi, v82
	s_and_b32 s28, s25, 0x8000
	s_xor_b32 s29, s28, 0x8000
	s_add_i32 s29, s29, vcc_hi
; __device__ __forceinline__ void gemm_mainloop_d(const bf16_t* __restrict__ Ap, int lda, const bf16_t* __restrict__ Bt, int K,
;                                                 int m0, int n0, f32x4 (&acc)[4][4], char* lds) {
;     ...
;   for (int kt = 0; kt < nk; kt++) {
;     const int st = kt & 1;
;     if (kt + 1 < nk) dma(kt + 1, st ^ 1);
;     const char* la = lds + st * 32768; const char* lb = la + 16384;
;     bf16x8 af[2][4], bfv[2][4];
; #pragma unroll
;     for (int kc = 0; kc < 2; kc++) {
; #pragma unroll
;       for (int m = 0; m < 4; m++) { const int row = wr * 64 + m * 16 + fr; af[kc][m] = *(const bf16x8*)(la + (row * 8 + ((kc * 4 + fq) ^ ((row >> 1) & 7))) * 16); }
; #pragma unroll
;       for (int n = 0; n < 4; n++) { const int row = wc * 64 + n * 16 + fr; bfv[kc][n] = *(const bf16x8*)(lb + (row * 8 + ((kc * 4 + fq) ^ ((row >> 1) & 7))) * 16); }
;     }
;     __builtin_amdgcn_s_setprio(1);
; #pragma unroll
;     for (int kc = 0; kc < 2; kc++)
; #pragma unroll
;       for (int m = 0; m < 4; m++)
; #pragma unroll
;         for (int n = 0; n < 4; n++) acc[m][n] = __builtin_amdgcn_mfma_f32_16x16x32_bf16(bfv[kc][n], af[kc][m], acc[m][n], 0, 0, 0);
;     __builtin_amdgcn_s_setprio(0);
;     asm volatile("s_waitcnt vmcnt(0) lgkmcnt(0)" ::: "memory"); __builtin_amdgcn_s_barrier(); asm volatile("" ::: "memory");
;   }
.LBB0_657:
	s_barrier
	s_setprio 3
	s_mov_b32 m0, s29
	s_add_i32 vcc_lo, s29, 0x4000
	global_load_lds_dwordx4 v150, s[46:47]
	s_mov_b32 m0, vcc_lo
	s_add_i32 vcc_lo, s29, 0x1000
	global_load_lds_dwordx4 v151, s[46:47]
	s_mov_b32 m0, vcc_lo
	s_add_i32 vcc_lo, s29, 0x5000
	global_load_lds_dwordx4 v152, s[46:47]
	s_mov_b32 m0, vcc_lo
	s_add_i32 vcc_lo, s29, 0x2000
	global_load_lds_dwordx4 v153, s[46:47]
	s_mov_b32 m0, vcc_lo
	s_add_i32 vcc_lo, s29, 0x6000
	global_load_lds_dwordx4 v154, s[46:47]
	s_mov_b32 m0, vcc_lo
	s_add_i32 vcc_lo, s29, 0x3000
	global_load_lds_dwordx4 v155, s[46:47]
	s_mov_b32 m0, vcc_lo
	s_add_i32 vcc_lo, s29, 0x7000
	global_load_lds_dwordx4 v156, s[46:47]
	s_mov_b32 m0, vcc_lo
	s_nop 0
	global_load_lds_dwordx4 v157, s[46:47]
	v_add_u32_e32 v150, 0x80, v150
	v_add_u32_e32 v151, 0x80, v151
	v_add_u32_e32 v152, 0x80, v152
	v_add_u32_e32 v153, 0x80, v153
	v_add_u32_e32 v154, 0x80, v154
	v_add_u32_e32 v155, 0x80, v155
	v_add_u32_e32 v156, 0x80, v156
	v_add_u32_e32 v157, 0x80, v157
	v_add_u32_e32 v98, s28, v85
	v_add_u32_e32 v114, s28, v84
	v_add_u32_e32 v130, s28, v83
	v_add_u32_e32 v146, s28, v2
	ds_read_b128 v[86:89], v98
	ds_read_b128 v[90:93], v98 offset:2048
	ds_read_b128 v[94:97], v98 offset:4096
	ds_read_b128 v[98:101], v98 offset:6144
	ds_read_b128 v[102:105], v114 offset:16384
	ds_read_b128 v[106:109], v114 offset:18432
	ds_read_b128 v[110:113], v114 offset:20480
	ds_read_b128 v[114:117], v114 offset:22528
	ds_read_b128 v[118:121], v130
	ds_read_b128 v[122:125], v130 offset:2048
	ds_read_b128 v[126:129], v130 offset:4096
	ds_read_b128 v[130:133], v130 offset:6144
	ds_read_b128 v[134:137], v146 offset:16384
	ds_read_b128 v[138:141], v146 offset:18432
	ds_read_b128 v[142:145], v146 offset:20480
	ds_read_b128 v[146:149], v146 offset:22528
	s_setprio 1
	s_waitcnt lgkmcnt(0)
	v_mfma_f32_16x16x32_bf16 v[64:67], v[102:105], v[86:89], v[64:67]
	v_mfma_f32_16x16x32_bf16 v[60:63], v[106:109], v[86:89], v[60:63]
	v_mfma_f32_16x16x32_bf16 v[56:59], v[110:113], v[86:89], v[56:59]
	v_mfma_f32_16x16x32_bf16 v[52:55], v[114:117], v[86:89], v[52:55]
	v_mfma_f32_16x16x32_bf16 v[48:51], v[102:105], v[90:93], v[48:51]
	v_mfma_f32_16x16x32_bf16 v[44:47], v[106:109], v[90:93], v[44:47]
	v_mfma_f32_16x16x32_bf16 v[40:43], v[110:113], v[90:93], v[40:43]
	v_mfma_f32_16x16x32_bf16 v[36:39], v[114:117], v[90:93], v[36:39]
	v_mfma_f32_16x16x32_bf16 v[32:35], v[102:105], v[94:97], v[32:35]
	v_mfma_f32_16x16x32_bf16 v[28:31], v[106:109], v[94:97], v[28:31]
	v_mfma_f32_16x16x32_bf16 v[24:27], v[110:113], v[94:97], v[24:27]
	v_mfma_f32_16x16x32_bf16 v[20:23], v[114:117], v[94:97], v[20:23]
	v_mfma_f32_16x16x32_bf16 v[16:19], v[102:105], v[98:101], v[16:19]
	v_mfma_f32_16x16x32_bf16 v[12:15], v[106:109], v[98:101], v[12:15]
	v_mfma_f32_16x16x32_bf16 v[8:11], v[110:113], v[98:101], v[8:11]
	v_mfma_f32_16x16x32_bf16 v[4:7], v[114:117], v[98:101], v[4:7]
	v_mfma_f32_16x16x32_bf16 v[64:67], v[134:137], v[118:121], v[64:67]
	v_mfma_f32_16x16x32_bf16 v[60:63], v[138:141], v[118:121], v[60:63]
	v_mfma_f32_16x16x32_bf16 v[56:59], v[142:145], v[118:121], v[56:59]
	v_mfma_f32_16x16x32_bf16 v[52:55], v[146:149], v[118:121], v[52:55]
	v_mfma_f32_16x16x32_bf16 v[48:51], v[134:137], v[122:125], v[48:51]
	v_mfma_f32_16x16x32_bf16 v[44:47], v[138:141], v[122:125], v[44:47]
	v_mfma_f32_16x16x32_bf16 v[40:43], v[142:145], v[122:125], v[40:43]
	v_mfma_f32_16x16x32_bf16 v[36:39], v[146:149], v[122:125], v[36:39]
	v_mfma_f32_16x16x32_bf16 v[32:35], v[134:137], v[126:129], v[32:35]
	v_mfma_f32_16x16x32_bf16 v[28:31], v[138:141], v[126:129], v[28:31]
	v_mfma_f32_16x16x32_bf16 v[24:27], v[142:145], v[126:129], v[24:27]
	v_mfma_f32_16x16x32_bf16 v[20:23], v[146:149], v[126:129], v[20:23]
	v_mfma_f32_16x16x32_bf16 v[16:19], v[134:137], v[130:133], v[16:19]
	v_mfma_f32_16x16x32_bf16 v[12:15], v[138:141], v[130:133], v[12:15]
	v_mfma_f32_16x16x32_bf16 v[8:11], v[142:145], v[130:133], v[8:11]
	v_mfma_f32_16x16x32_bf16 v[4:7], v[146:149], v[130:133], v[4:7]
	s_setprio 0
	s_waitcnt vmcnt(0) lgkmcnt(0)
	s_add_u32 s26, s26, 0x80
	s_addc_u32 s27, s27, 0
	s_add_i32 s25, s25, 0x8000
	s_and_b32 s28, s25, 0x8000
	s_xor_b32 s29, s28, 0x8000
	s_add_i32 s29, s29, vcc_hi
	s_cmpk_eq_i32 s26, 0x780
	s_cbranch_scc0 .LBB0_657
	s_barrier
; __device__ __forceinline__ unsigned pk2(float lo, float hi) { unsigned r; asm("v_cvt_pk_bf16_f32 %0, %1, %2" : "=v"(r) : "v"(lo), "v"(hi)); return r; }
; __device__ __forceinline__ float bflo(unsigned u) { return __uint_as_float(u << 16); }
; __device__ __forceinline__ float bfhi(unsigned u) { return __uint_as_float(u & 0xffff0000u); }
; __device__ __forceinline__ void gemm_mainloop_d(const bf16_t* __restrict__ Ap, int lda, const bf16_t* __restrict__ Bt, int K,
;                                                 int m0, int n0, f32x4 (&acc)[4][4], char* lds) {
;     ...
;     const char* la = lds + st * 32768; const char* lb = la + 16384;
;     bf16x8 af[2][4], bfv[2][4];
; #pragma unroll
;     for (int kc = 0; kc < 2; kc++) {
; #pragma unroll
;       for (int m = 0; m < 4; m++) { const int row = wr * 64 + m * 16 + fr; af[kc][m] = *(const bf16x8*)(la + (row * 8 + ((kc * 4 + fq) ^ ((row >> 1) & 7))) * 16); }
; #pragma unroll
;       for (int n = 0; n < 4; n++) { const int row = wc * 64 + n * 16 + fr; bfv[kc][n] = *(const bf16x8*)(lb + (row * 8 + ((kc * 4 + fq) ^ ((row >> 1) & 7))) * 16); }
;     }
;     __builtin_amdgcn_s_setprio(1);
; #pragma unroll
;     for (int kc = 0; kc < 2; kc++)
; #pragma unroll
;       for (int m = 0; m < 4; m++)
; #pragma unroll
;         for (int n = 0; n < 4; n++) acc[m][n] = __builtin_amdgcn_mfma_f32_16x16x32_bf16(bfv[kc][n], af[kc][m], acc[m][n], 0, 0, 0);
;     __builtin_amdgcn_s_setprio(0);
;     asm volatile("s_waitcnt vmcnt(0) lgkmcnt(0)" ::: "memory"); __builtin_amdgcn_s_barrier(); asm volatile("" ::: "memory");
; __device__ __forceinline__ void gemm_A(const Params& p, int item, char* lds) {
;     ...
; #pragma unroll
;   for (int m = 0; m < 4; m++) {
;     const int rl = wr * 64 + m * 16 + fr; const float r = rsqrtf(rssg[rl] * (1.f / 1024.f) + 1e-6f);
;     float sq = 0.f;
; #pragma unroll
;     for (int n = 0; n < 4; n++) {
;       const int col = n0 + wc * 64 + n * 16 + fq * 4;
;       if (col < PIN) { f32x4 v = acc[m][n] * r; u32x2 w; w[0] = pk2(v[0], v[1]); w[1] = pk2(v[2], v[3]); *(u32x2*)(P + (size_t)(m0 + rl) * PIN + col) = w;
;         const float b0 = bflo(w[0]), b1 = bfhi(w[0]), b2 = bflo(w[1]), b3 = bfhi(w[1]); sq += b0 * b0 + b1 * b1 + b2 * b2 + b3 * b3; }
	v_add_u32_e32 v0, 0, v85
	ds_read_b128 v[68:71], v0 offset:32768
	ds_read_b128 v[72:75], v0 offset:34816
	ds_read_b128 v[76:79], v0 offset:36864
	ds_read_b128 v[86:89], v0 offset:38912
	v_add_u32_e32 v0, 0, v84
	ds_read_b128 v[90:93], v0 offset:49152
	ds_read_b128 v[94:97], v0 offset:51200
	ds_read_b128 v[98:101], v0 offset:53248
	ds_read_b128 v[102:105], v0 offset:55296
	v_add_u32_e32 v0, 0, v83
	ds_read_b128 v[80:83], v0 offset:32768
	ds_read_b128 v[106:109], v0 offset:34816
	ds_read_b128 v[110:113], v0 offset:36864
	ds_read_b128 v[114:117], v0 offset:38912
	v_add_u32_e32 v0, 0, v2
	ds_read_b128 v[118:121], v0 offset:49152
	ds_read_b128 v[122:125], v0 offset:51200
	ds_read_b128 v[126:129], v0 offset:53248
	ds_read_b128 v[130:133], v0 offset:55296
	s_setprio 1
	s_waitcnt lgkmcnt(0)
	v_mfma_f32_16x16x32_bf16 v[64:67], v[90:93], v[68:71], v[64:67]
	v_mfma_f32_16x16x32_bf16 v[60:63], v[94:97], v[68:71], v[60:63]
	v_mfma_f32_16x16x32_bf16 v[56:59], v[98:101], v[68:71], v[56:59]
	v_mfma_f32_16x16x32_bf16 v[52:55], v[102:105], v[68:71], v[52:55]
	v_mfma_f32_16x16x32_bf16 v[48:51], v[90:93], v[72:75], v[48:51]
	v_mfma_f32_16x16x32_bf16 v[44:47], v[94:97], v[72:75], v[44:47]
	v_mfma_f32_16x16x32_bf16 v[40:43], v[98:101], v[72:75], v[40:43]
	v_mfma_f32_16x16x32_bf16 v[36:39], v[102:105], v[72:75], v[36:39]
	v_mfma_f32_16x16x32_bf16 v[32:35], v[90:93], v[76:79], v[32:35]
	v_mfma_f32_16x16x32_bf16 v[28:31], v[94:97], v[76:79], v[28:31]
	v_mfma_f32_16x16x32_bf16 v[24:27], v[98:101], v[76:79], v[24:27]
	v_mfma_f32_16x16x32_bf16 v[20:23], v[102:105], v[76:79], v[20:23]
	v_mfma_f32_16x16x32_bf16 v[16:19], v[90:93], v[86:89], v[16:19]
	v_mfma_f32_16x16x32_bf16 v[12:15], v[94:97], v[86:89], v[12:15]
	v_mfma_f32_16x16x32_bf16 v[8:11], v[98:101], v[86:89], v[8:11]
	v_mfma_f32_16x16x32_bf16 v[4:7], v[102:105], v[86:89], v[4:7]
	v_mfma_f32_16x16x32_bf16 v[64:67], v[118:121], v[80:83], v[64:67]
	v_mfma_f32_16x16x32_bf16 v[60:63], v[122:125], v[80:83], v[60:63]
	v_mfma_f32_16x16x32_bf16 v[56:59], v[126:129], v[80:83], v[56:59]
	v_mfma_f32_16x16x32_bf16 v[52:55], v[130:133], v[80:83], v[52:55]
	v_mfma_f32_16x16x32_bf16 v[48:51], v[118:121], v[106:109], v[48:51]
	v_mfma_f32_16x16x32_bf16 v[44:47], v[122:125], v[106:109], v[44:47]
	v_mfma_f32_16x16x32_bf16 v[40:43], v[126:129], v[106:109], v[40:43]
	v_mfma_f32_16x16x32_bf16 v[36:39], v[130:133], v[106:109], v[36:39]
	v_mfma_f32_16x16x32_bf16 v[32:35], v[118:121], v[110:113], v[32:35]
	v_mfma_f32_16x16x32_bf16 v[28:31], v[122:125], v[110:113], v[28:31]
	v_mfma_f32_16x16x32_bf16 v[24:27], v[126:129], v[110:113], v[24:27]
	v_mfma_f32_16x16x32_bf16 v[20:23], v[130:133], v[110:113], v[20:23]
	v_mfma_f32_16x16x32_bf16 v[16:19], v[118:121], v[114:117], v[16:19]
	v_mfma_f32_16x16x32_bf16 v[12:15], v[122:125], v[114:117], v[12:15]
	v_mfma_f32_16x16x32_bf16 v[8:11], v[126:129], v[114:117], v[8:11]
	v_mfma_f32_16x16x32_bf16 v[4:7], v[130:133], v[114:117], v[4:7]
	s_setprio 0
	v_mov_b32_e32 v2, v198
	s_mov_b32 s25, s89
	s_waitcnt vmcnt(0) lgkmcnt(0)
	s_barrier
	s_add_u32 s28, s46, s25
	s_addc_u32 s29, s47, 0
	s_ashr_i32 s25, s24, 31
	v_and_b32_e32 v0, 15, v2
	s_lshl_b64 s[26:27], s[24:25], 2
	v_ashrrev_i32_e32 v1, 1, v2
	s_movk_i32 s4, 0xffc0
	s_add_u32 s28, s28, s26
	v_and_or_b32 v0, v1, s4, v0
	s_addc_u32 s29, s29, s27
	v_ashrrev_i32_e32 v1, 31, v0
	v_lshl_add_u64 v[70:71], v[0:1], 2, s[28:29]
	s_mov_b32 s28, 0xff8c000
	v_add_co_u32_e32 v68, vcc, s28, v70
	s_mov_b32 s25, s89
	s_nop 0
	v_addc_co_u32_e32 v69, vcc, 0, v71, vcc
	global_load_dword v69, v[68:69], off
	v_and_b32_e32 v68, 64, v2
	v_bfe_u32 v2, v2, 4, 2
	v_lshlrev_b32_e32 v72, 2, v2
	v_or3_b32 v68, v72, v68, s3
	s_add_u32 s3, s46, s25
	s_addc_u32 s25, s47, 0
	s_add_u32 s30, s3, 0x768000
	s_addc_u32 s31, s25, 0
	v_add_u32_e32 v74, s24, v0
	v_mov_b32_e32 v76, 0
	v_cmp_gt_i32_e64 s[34:35], s78, v68
	s_waitcnt vmcnt(0)
	v_fmamk_f32 v69, v69, 0x3a800000, v200
	v_mul_f32_e32 v72, 0x4b800000, v69
	v_cmp_gt_f32_e32 vcc, s83, v69
	s_nop 1
	v_cndmask_b32_e32 v69, v69, v72, vcc
	v_rsq_f32_e32 v69, v69
	v_mov_b64_e32 v[72:73], s[30:31]
	v_mad_i64_i32 v[72:73], s[28:29], v74, s69, v[72:73]
	v_mul_f32_e32 v74, 0x45800000, v69
	v_cndmask_b32_e32 v74, v69, v74, vcc
	v_mov_b32_e32 v75, v74
	v_ashrrev_i32_e32 v69, 31, v68
	s_and_saveexec_b64 s[28:29], s[34:35]
	s_cbranch_execz .LBB0_660
	v_mov_b32_e32 v76, v74
	v_mov_b32_e32 v77, v74
	v_pk_mul_f32 v[66:67], v[66:67], v[76:77]
	v_pk_mul_f32 v[64:65], v[64:65], v[74:75]
	s_nop 0
	v_cvt_pk_bf16_f32 v64, v64, v65
	v_cvt_pk_bf16_f32 v65, v66, v67
	v_lshl_add_u64 v[66:67], v[68:69], 1, v[72:73]
	global_store_dwordx2 v[66:67], v[64:65], off
	v_lshlrev_b32_e32 v66, 16, v64
	v_and_b32_e32 v67, 0xffff0000, v64
	v_pk_mul_f32 v[66:67], v[66:67], v[66:67]
	v_and_b32_e32 v64, 0xffff0000, v65
	v_lshlrev_b32_e32 v65, 16, v65
	v_pk_mul_f32 v[64:65], v[64:65], v[64:65]
	v_add_f32_e32 v66, v66, v67
	v_add_f32_e32 v65, v66, v65
	v_add_f32_e32 v76, v64, v65
